# grid barrier: acquire (buffer_inv sc1) issued as soon as the workgroup's own part of the barrier protocol is sent (before polling) so it overlaps the wait
# speedup vs baseline: 1.0579x; 1.0202x over previous
.LBB0_162:
	v_mov_b32_e32 v2, 0x20000
	ds_read_b32 v6, v2
	ds_read_b32 v7, v2 offset:4
	v_readlane_b32 s0, v255, 2
	s_and_b32 s0, s0, 7
	s_lshl_b32 s0, s0, 7
	s_add_i32 s0, s0, 0x3600
	v_mov_b32_e32 v8, s0
	v_mov_b32_e32 v9, 1
	s_mov_b32 s11, 1
	s_mov_b32 s10, 0
	global_atomic_add v10, v8, v9, s[70:71] sc0
	s_waitcnt vmcnt(0) lgkmcnt(0)
	v_mul_lo_u32 v11, v6, s11
	v_add_u32_e32 v10, 1, v10
	v_cmp_eq_u32_e32 vcc, v10, v11
	v_mul_lo_u32 v11, v7, s11
	s_cbranch_vccz .Lxb1_inv
	buffer_wbl2 sc1
	v_mov_b32_e32 v2, 0x3a00
	s_waitcnt vmcnt(0)
	global_atomic_add v2, v9, s[70:71]
	global_atomic_add v2, v9, s[70:71] offset:128
	global_atomic_add v2, v9, s[70:71] offset:256
	global_atomic_add v2, v9, s[70:71] offset:384
	global_atomic_add v2, v9, s[70:71] offset:512
	global_atomic_add v2, v9, s[70:71] offset:640
	global_atomic_add v2, v9, s[70:71] offset:768
	global_atomic_add v2, v9, s[70:71] offset:896
.Lxb1_inv:
	buffer_inv sc1
.Lxb1_poll:
	global_load_dword v10, v8, s[70:71] offset:1024 sc1
	s_add_i32 s10, s10, 1
	s_waitcnt vmcnt(0)
	v_cmp_ge_u32_e32 vcc, v10, v11
	s_cbranch_vccnz .Lxb1_done
	s_sleep 1
	s_cmp_lt_u32 s10, 0x8000
	s_cbranch_scc1 .Lxb1_poll
.Lxb1_done:
.LBB0_198:
	s_or_b64 exec, exec, s[4:5]
	s_add_u32 s44, s70, 0x7800000
	s_addc_u32 s45, s71, 0
	s_cmpk_gt_i32 s96, 0xff
	s_cselect_b64 s[4:5], -1, 0
	s_bitcmp0_b32 s35, 6
	s_cselect_b64 s[0:1], -1, 0
	s_cmpk_lt_i32 s68, 0x800
	s_cselect_b64 s[6:7], -1, 0
	s_and_b64 s[0:1], s[0:1], s[6:7]
	s_and_b64 s[0:1], s[4:5], s[0:1]
	s_andn2_b64 vcc, exec, s[0:1]
	s_waitcnt lgkmcnt(0)
	s_barrier
	v_lshlrev_b32_e32 v1, 4, v170
	v_add_u32_e32 v2, 0x1000, v1
	v_lshlrev_b32_e32 v3, 3, v170
	s_lshr_b32 s0, s68, 9
	s_lshl_b32 s0, s0, 16
	s_add_u32 s32, s14, s0
	s_addc_u32 s33, s15, 0
	s_lshl_b32 s0, s68, 15
	s_add_u32 s10, s52, s0
	s_addc_u32 s11, s53, 0
	s_lshl_b32 s0, s68, 14
	s_add_u32 s12, s70, s0
	s_addc_u32 s13, s71, 0
	s_add_u32 s12, s12, 0x7800000
	s_addc_u32 s13, s13, 0
	v_mul_u32_u24_e32 v77, 0x1556, v170
	v_lshrrev_b32_e32 v77, 16, v77
	v_lshlrev_b32_e32 v80, 4, v170
	v_lshl_add_u32 v171, v77, 6, v80
	v_add_u32_e32 v75, 0x40, v170
	v_mul_u32_u24_e32 v77, 0x1556, v75
	v_lshrrev_b32_e32 v77, 16, v77
	v_lshlrev_b32_e32 v80, 4, v75
	v_lshl_add_u32 v172, v77, 6, v80
	v_add_u32_e32 v75, 0x80, v170
	v_mul_u32_u24_e32 v77, 0x1556, v75
	v_lshrrev_b32_e32 v77, 16, v77
	v_lshlrev_b32_e32 v80, 4, v75
	v_lshl_add_u32 v173, v77, 6, v80
	v_add_u32_e32 v75, 0xc0, v170
	v_mul_u32_u24_e32 v77, 0x1556, v75
	v_lshrrev_b32_e32 v77, 16, v77
	v_lshlrev_b32_e32 v80, 4, v75
	v_lshl_add_u32 v174, v77, 6, v80
	v_add_u32_e32 v75, 0x100, v170
	v_mul_u32_u24_e32 v77, 0x1556, v75
	v_lshrrev_b32_e32 v77, 16, v77
	v_lshlrev_b32_e32 v80, 4, v75
	v_lshl_add_u32 v175, v77, 6, v80
	v_add_u32_e32 v75, 0x140, v170
	v_mul_u32_u24_e32 v77, 0x1556, v75
	v_lshrrev_b32_e32 v77, 16, v77
	v_lshlrev_b32_e32 v80, 4, v75
	v_lshl_add_u32 v176, v77, 6, v80
	v_add_u32_e32 v75, 0x180, v170
	v_mul_u32_u24_e32 v77, 0x1556, v75
	v_lshrrev_b32_e32 v77, 16, v77
	v_lshlrev_b32_e32 v80, 4, v75
	v_lshl_add_u32 v177, v77, 6, v80
	v_add_u32_e32 v75, 0x1c0, v170
	v_mul_u32_u24_e32 v77, 0x1556, v75
	v_lshrrev_b32_e32 v77, 16, v77
	v_lshlrev_b32_e32 v80, 4, v75
	v_lshl_add_u32 v178, v77, 6, v80
	v_add_u32_e32 v75, 0x200, v170
	v_mul_u32_u24_e32 v77, 0x1556, v75
	v_lshrrev_b32_e32 v77, 16, v77
	v_lshlrev_b32_e32 v80, 4, v75
	v_lshl_add_u32 v179, v77, 6, v80
	v_add_u32_e32 v75, 0x240, v170
	v_mul_u32_u24_e32 v77, 0x1556, v75
	v_lshrrev_b32_e32 v77, 16, v77
	v_lshlrev_b32_e32 v80, 4, v75
	v_lshl_add_u32 v180, v77, 6, v80
	v_add_u32_e32 v75, 0x280, v170
	v_mul_u32_u24_e32 v77, 0x1556, v75
	v_lshrrev_b32_e32 v77, 16, v77
	v_lshlrev_b32_e32 v80, 4, v75
	v_lshl_add_u32 v181, v77, 6, v80
	v_add_u32_e32 v75, 0x2c0, v170
	v_mul_u32_u24_e32 v77, 0x1556, v75
	v_lshrrev_b32_e32 v77, 16, v77
	v_lshlrev_b32_e32 v80, 4, v75
	v_lshl_add_u32 v182, v77, 6, v80
	v_add_u32_e32 v75, 0x300, v170
	v_mul_u32_u24_e32 v77, 0x1556, v75
	v_lshrrev_b32_e32 v77, 16, v77
	v_lshlrev_b32_e32 v80, 4, v75
	v_lshl_add_u32 v183, v77, 6, v80
	v_add_u32_e32 v75, 0x340, v170
	v_mul_u32_u24_e32 v77, 0x1556, v75
	v_lshrrev_b32_e32 v77, 16, v77
	v_lshlrev_b32_e32 v80, 4, v75
	v_lshl_add_u32 v162, v77, 6, v80
	v_add_u32_e32 v75, 0x380, v170
	v_mul_u32_u24_e32 v77, 0x1556, v75
	v_lshrrev_b32_e32 v77, 16, v77
	v_lshlrev_b32_e32 v80, 4, v75
	v_lshl_add_u32 v163, v77, 6, v80
	v_add_u32_e32 v75, 0x3c0, v170
	v_mul_u32_u24_e32 v77, 0x1556, v75
	v_lshrrev_b32_e32 v77, 16, v77
	v_lshlrev_b32_e32 v80, 4, v75
	v_lshl_add_u32 v164, v77, 6, v80
	global_load_dwordx4 v[186:189], v171, s[32:33]
	global_load_dwordx4 v[190:193], v172, s[32:33]
	global_load_dwordx4 v[194:197], v173, s[32:33]
	global_load_dwordx4 v[198:201], v174, s[32:33]
	global_load_dwordx4 v[202:205], v175, s[32:33]
	global_load_dwordx4 v[206:209], v176, s[32:33]
	global_load_dwordx4 v[210:213], v177, s[32:33]
	global_load_dwordx4 v[214:217], v178, s[32:33]
	global_load_dwordx4 v[218:221], v179, s[32:33]
	global_load_dwordx4 v[222:225], v180, s[32:33]
	global_load_dwordx4 v[226:229], v181, s[32:33]
	global_load_dwordx4 v[230:233], v182, s[32:33]
	global_load_dwordx4 v[234:237], v183, s[32:33]
	global_load_dwordx4 v[238:241], v162, s[32:33]
	global_load_dwordx4 v[242:245], v163, s[32:33]
	global_load_dwordx4 v[246:249], v164, s[32:33]
	global_load_dwordx4 v[6:9], v1, s[10:11] nt
	global_load_dwordx4 v[10:13], v1, s[10:11] offset:1024 nt
	global_load_dwordx4 v[14:17], v1, s[10:11] offset:2048 nt
	global_load_dwordx4 v[18:21], v1, s[10:11] offset:3072 nt
	global_load_dwordx4 v[22:25], v2, s[10:11] nt
	global_load_dwordx4 v[26:29], v2, s[10:11] offset:1024 nt
	global_load_dwordx4 v[30:33], v2, s[10:11] offset:2048 nt
	global_load_dwordx4 v[34:37], v2, s[10:11] offset:3072 nt
	s_add_u32 s10, s10, 0x2000
	s_addc_u32 s11, s11, 0
	global_load_dwordx4 v[38:41], v1, s[10:11] nt
	global_load_dwordx4 v[42:45], v1, s[10:11] offset:1024 nt
	global_load_dwordx4 v[46:49], v1, s[10:11] offset:2048 nt
	global_load_dwordx4 v[50:53], v1, s[10:11] offset:3072 nt
	global_load_dwordx4 v[54:57], v2, s[10:11] nt
	global_load_dwordx4 v[58:61], v2, s[10:11] offset:1024 nt
	global_load_dwordx4 v[62:65], v2, s[10:11] offset:2048 nt
	global_load_dwordx4 v[66:69], v2, s[10:11] offset:3072 nt
	s_add_u32 s10, s10, 0x2000
	s_addc_u32 s11, s11, 0
	global_load_dwordx4 v[94:97], v1, s[10:11] nt
	global_load_dwordx4 v[98:101], v1, s[10:11] offset:1024 nt
	global_load_dwordx4 v[102:105], v1, s[10:11] offset:2048 nt
	global_load_dwordx4 v[106:109], v1, s[10:11] offset:3072 nt
	global_load_dwordx4 v[110:113], v2, s[10:11] nt
	global_load_dwordx4 v[114:117], v2, s[10:11] offset:1024 nt
	global_load_dwordx4 v[118:121], v2, s[10:11] offset:2048 nt
	global_load_dwordx4 v[122:125], v2, s[10:11] offset:3072 nt
	s_add_u32 s10, s10, 0x2000
	s_addc_u32 s11, s11, 0
	global_load_dwordx4 v[126:129], v1, s[10:11] nt
	global_load_dwordx4 v[130:133], v1, s[10:11] offset:1024 nt
	global_load_dwordx4 v[134:137], v1, s[10:11] offset:2048 nt
	global_load_dwordx4 v[138:141], v1, s[10:11] offset:3072 nt
	global_load_dwordx4 v[142:145], v2, s[10:11] nt
	global_load_dwordx4 v[146:149], v2, s[10:11] offset:1024 nt
	global_load_dwordx4 v[150:153], v2, s[10:11] offset:2048 nt
	global_load_dwordx4 v[154:157], v2, s[10:11] offset:3072 nt
	s_lshr_b32 s0, s68, 4
	s_bfe_u32 s3, s68, 0x30001
	s_lshl_b32 s6, s0, 13
	s_lshl_b32 s9, s3, 10
	s_add_u32 s6, s6, s9
	s_add_u32 s38, s54, s6
	s_addc_u32 s39, s55, 0
	s_add_u32 s6, s0, 4
	s_lshl_b32 s6, s6, 16
	s_add_u32 s74, s14, s6
	s_addc_u32 s75, s15, 0
	s_lshl_b32 s6, s0, 12
	s_lshl_b32 s9, s3, 9
	s_add_u32 s6, s6, s9
	s_add_u32 s6, s6, 0x9800000
	s_add_u32 s88, s70, s6
	s_addc_u32 s89, s71, 0
	s_lshl_b32 s9, s3, 6
	s_waitcnt vmcnt(32)
	v_pk_add_f32 v[218:219], v[218:219], 1.0 op_sel_hi:[1,0]
	v_pk_add_f32 v[220:221], v[220:221], 1.0 op_sel_hi:[1,0]
	v_pk_add_f32 v[222:223], v[222:223], 1.0 op_sel_hi:[1,0]
	v_pk_add_f32 v[224:225], v[224:225], 1.0 op_sel_hi:[1,0]
	v_pk_add_f32 v[226:227], v[226:227], 1.0 op_sel_hi:[1,0]
	v_pk_add_f32 v[228:229], v[228:229], 1.0 op_sel_hi:[1,0]
	v_pk_add_f32 v[230:231], v[230:231], 1.0 op_sel_hi:[1,0]
	v_pk_add_f32 v[232:233], v[232:233], 1.0 op_sel_hi:[1,0]
	v_pk_add_f32 v[234:235], v[234:235], 1.0 op_sel_hi:[1,0]
	v_pk_add_f32 v[236:237], v[236:237], 1.0 op_sel_hi:[1,0]
	v_pk_add_f32 v[238:239], v[238:239], 1.0 op_sel_hi:[1,0]
	v_pk_add_f32 v[240:241], v[240:241], 1.0 op_sel_hi:[1,0]
	v_pk_add_f32 v[242:243], v[242:243], 1.0 op_sel_hi:[1,0]
	v_pk_add_f32 v[244:245], v[244:245], 1.0 op_sel_hi:[1,0]
	v_pk_add_f32 v[246:247], v[246:247], 1.0 op_sel_hi:[1,0]
	v_pk_add_f32 v[248:249], v[248:249], 1.0 op_sel_hi:[1,0]
	s_waitcnt vmcnt(31)
	v_pk_fma_f32 v[6:7], v[6:7], v[218:219], v[186:187]
	v_pk_fma_f32 v[8:9], v[8:9], v[220:221], v[188:189]
	v_cvt_pk_bf16_f32 v6, v6, v7
	v_cvt_pk_bf16_f32 v7, v8, v9
	global_store_dwordx2 v3, v[6:7], s[12:13]
	s_waitcnt vmcnt(31)
	v_pk_fma_f32 v[10:11], v[10:11], v[222:223], v[190:191]
	v_pk_fma_f32 v[12:13], v[12:13], v[224:225], v[192:193]
	v_cvt_pk_bf16_f32 v10, v10, v11
	v_cvt_pk_bf16_f32 v11, v12, v13
	global_store_dwordx2 v3, v[10:11], s[12:13] offset:512
	s_waitcnt vmcnt(31)
	v_pk_fma_f32 v[14:15], v[14:15], v[226:227], v[194:195]
	v_pk_fma_f32 v[16:17], v[16:17], v[228:229], v[196:197]
	v_cvt_pk_bf16_f32 v14, v14, v15
	v_cvt_pk_bf16_f32 v15, v16, v17
	global_store_dwordx2 v3, v[14:15], s[12:13] offset:1024
	s_waitcnt vmcnt(31)
	v_pk_fma_f32 v[18:19], v[18:19], v[230:231], v[198:199]
	v_pk_fma_f32 v[20:21], v[20:21], v[232:233], v[200:201]
	v_cvt_pk_bf16_f32 v18, v18, v19
	v_cvt_pk_bf16_f32 v19, v20, v21
	global_store_dwordx2 v3, v[18:19], s[12:13] offset:1536
	s_waitcnt vmcnt(31)
	v_pk_fma_f32 v[22:23], v[22:23], v[234:235], v[202:203]
	v_pk_fma_f32 v[24:25], v[24:25], v[236:237], v[204:205]
	v_cvt_pk_bf16_f32 v22, v22, v23
	v_cvt_pk_bf16_f32 v23, v24, v25
	global_store_dwordx2 v3, v[22:23], s[12:13] offset:2048
	s_waitcnt vmcnt(31)
	v_pk_fma_f32 v[26:27], v[26:27], v[238:239], v[206:207]
	v_pk_fma_f32 v[28:29], v[28:29], v[240:241], v[208:209]
	v_cvt_pk_bf16_f32 v26, v26, v27
	v_cvt_pk_bf16_f32 v27, v28, v29
	global_store_dwordx2 v3, v[26:27], s[12:13] offset:2560
	s_waitcnt vmcnt(31)
	v_pk_fma_f32 v[30:31], v[30:31], v[242:243], v[210:211]
	v_pk_fma_f32 v[32:33], v[32:33], v[244:245], v[212:213]
	v_cvt_pk_bf16_f32 v30, v30, v31
	v_cvt_pk_bf16_f32 v31, v32, v33
	global_store_dwordx2 v3, v[30:31], s[12:13] offset:3072
	s_waitcnt vmcnt(31)
	v_pk_fma_f32 v[34:35], v[34:35], v[246:247], v[214:215]
	v_pk_fma_f32 v[36:37], v[36:37], v[248:249], v[216:217]
	v_cvt_pk_bf16_f32 v34, v34, v35
	v_cvt_pk_bf16_f32 v35, v36, v37
	global_store_dwordx2 v3, v[34:35], s[12:13] offset:3584
	s_add_u32 s12, s12, 0x1000
	s_addc_u32 s13, s13, 0
	s_bitcmp1_b32 s68, 0
	s_cbranch_scc1 .Lp1_odd_a
	v_add_u32_e32 v75, s9, v170
	v_mul_u32_u24_e32 v77, 0x1556, v75
	v_lshrrev_b32_e32 v77, 16, v77
	v_lshlrev_b32_e32 v80, 4, v75
	v_lshl_add_u32 v165, v77, 6, v80
	v_add_u32_e32 v75, 0x200, v75
	v_mul_u32_u24_e32 v77, 0x1556, v75
	v_lshrrev_b32_e32 v77, 16, v77
	v_lshlrev_b32_e32 v80, 4, v75
	v_lshl_add_u32 v166, v77, 6, v80
	global_load_dwordx4 v[6:9], v1, s[38:39]
	global_load_dwordx4 v[10:13], v165, s[74:75]
	global_load_dwordx4 v[14:17], v166, s[74:75]

.LBB0_203:
	s_waitcnt vmcnt(0)
	s_barrier
	s_mov_b64 s[4:5], exec
	v_readlane_b32 s0, v255, 3
	s_mov_b32 s6, s68
	v_readlane_b32 s1, v255, 4
	v_writelane_b32 v255, s6, 10
	s_and_b64 s[0:1], s[4:5], s[0:1]
	s_nop 0
	v_writelane_b32 v255, s7, 11
	s_mov_b64 exec, s[0:1]
	s_cbranch_execz .LBB0_255
	v_mov_b32_e32 v2, 0x20000
	ds_read_b32 v6, v2
	ds_read_b32 v7, v2 offset:4
	v_readlane_b32 s0, v255, 2
	s_and_b32 s0, s0, 7
	s_lshl_b32 s0, s0, 7
	s_add_i32 s0, s0, 0x3600
	v_mov_b32_e32 v8, s0
	v_mov_b32_e32 v9, 1
	s_mov_b32 s11, 2
	s_mov_b32 s10, 0
	global_atomic_add v10, v8, v9, s[70:71] sc0
	s_waitcnt vmcnt(0) lgkmcnt(0)
	v_mul_lo_u32 v11, v6, s11
	v_add_u32_e32 v10, 1, v10
	v_cmp_eq_u32_e32 vcc, v10, v11
	v_mul_lo_u32 v11, v7, s11
	s_cbranch_vccz .Lxb2_inv
	buffer_wbl2 sc1
	v_mov_b32_e32 v2, 0x3a00
	s_waitcnt vmcnt(0)
	global_atomic_add v2, v9, s[70:71]
	global_atomic_add v2, v9, s[70:71] offset:128
	global_atomic_add v2, v9, s[70:71] offset:256
	global_atomic_add v2, v9, s[70:71] offset:384
	global_atomic_add v2, v9, s[70:71] offset:512
	global_atomic_add v2, v9, s[70:71] offset:640
	global_atomic_add v2, v9, s[70:71] offset:768
	global_atomic_add v2, v9, s[70:71] offset:896
.Lxb2_inv:
	buffer_inv sc1
.Lxb2_poll:
	global_load_dword v10, v8, s[70:71] offset:1024 sc1
	s_add_i32 s10, s10, 1
	s_waitcnt vmcnt(0)
	v_cmp_ge_u32_e32 vcc, v10, v11
	s_cbranch_vccnz .Lxb2_done
	s_sleep 1
	s_cmp_lt_u32 s10, 0x8000
	s_cbranch_scc1 .Lxb2_poll
.Lxb2_done:
.LBB0_255:
	s_or_b64 exec, exec, s[4:5]
	s_waitcnt lgkmcnt(0)
	v_lshlrev_b32_e32 v1, 4, v0
	v_and_b32_e32 v2, 32, v0
	s_add_u32 s38, s70, 0x9900000
	v_bitop3_b32 v192, v1, v2, 48 bitop3:0x6c
	v_lshrrev_b32_e32 v2, 5, v0
	v_lshrrev_b32_e32 v4, 1, v0
	v_or_b32_e32 v195, 0x2000, v1
	s_addc_u32 s39, s71, 0
	v_bfe_u32 v194, v0, 2, 4
	v_and_b32_e32 v2, 4, v2
	v_bfe_u32 v3, v0, 2, 2
	v_and_b32_e32 v200, 24, v4
	v_lshrrev_b32_e32 v1, 7, v195
	s_movk_i32 s0, 0x70
	v_or3_b32 v2, v2, v3, v200
	v_and_or_b32 v198, v1, s0, v194
	s_movk_i32 s0, 0x60
	s_cmpk_lt_i32 s2, 0x400
	v_and_b32_e32 v193, 64, v0
	v_lshrrev_b32_e32 v3, 3, v0
	v_and_or_b32 v141, v1, s0, v2
	v_lshlrev_b32_e32 v1, 6, v0
	v_lshlrev_b32_e32 v160, 2, v0
	s_cselect_b64 s[0:1], -1, 0
	v_or_b32_e32 v196, v192, v193
	v_and_or_b32 v197, v3, 48, v194
	v_and_or_b32 v140, v3, 32, v2
	v_lshlrev_b32_e32 v201, 1, v200
	v_and_b32_e32 v208, 0x3c0, v1
	v_and_b32_e32 v206, 32, v160
	v_writelane_b32 v255, s0, 12
	v_readfirstlane_b32 s10, v0
	v_lshl_or_b32 v150, v197, 12, v196
	v_lshl_or_b32 v154, v140, 12, v196
	v_lshl_or_b32 v152, v198, 12, v196
	v_lshl_or_b32 v156, v141, 12, v196
	v_and_b32_e32 v207, 15, v0
	v_writelane_b32 v255, s1, 13
	s_cmpk_gt_i32 s2, 0x3ff
	v_bitop3_b32 v202, v201, v206, v208 bitop3:0x36
	s_barrier
	s_cbranch_scc1 .LBB0_279
	s_ashr_i32 s0, s2, 31
	s_lshr_b32 s1, s0, 29
	s_add_i32 s1, s2, s1
	s_and_b32 s3, s1, -8
	s_sub_i32 s6, s2, s3
	s_cmp_gt_i32 s6, -1
	s_cbranch_scc0 .LBB0_258
	s_lshl_b32 s3, s6, 7
	s_cbranch_execz .LBB0_259
	s_branch .LBB0_260

.LBB0_297:
	s_waitcnt vmcnt(0)
	s_waitcnt vmcnt(0)
	s_barrier
	s_mov_b64 s[4:5], exec
	v_readlane_b32 s0, v255, 3
	v_readlane_b32 s1, v255, 4
	s_and_b64 s[0:1], s[4:5], s[0:1]
	s_mov_b64 exec, s[0:1]
	s_cbranch_execz .LBB0_349
	v_mov_b32_e32 v2, 0x20000
	ds_read_b32 v6, v2
	ds_read_b32 v7, v2 offset:4
	v_readlane_b32 s0, v255, 2
	s_and_b32 s0, s0, 7
	s_lshl_b32 s0, s0, 7
	s_add_i32 s0, s0, 0x3600
	v_mov_b32_e32 v8, s0
	v_mov_b32_e32 v9, 1
	s_mov_b32 s11, 3
	s_mov_b32 s10, 0
	global_atomic_add v10, v8, v9, s[70:71] sc0
	s_waitcnt vmcnt(0) lgkmcnt(0)
	v_mul_lo_u32 v11, v6, s11
	v_add_u32_e32 v10, 1, v10
	v_cmp_eq_u32_e32 vcc, v10, v11
	v_mul_lo_u32 v11, v7, s11
	s_cbranch_vccz .Lxb3_inv
	buffer_wbl2 sc1
	v_mov_b32_e32 v2, 0x3a00
	s_waitcnt vmcnt(0)
	global_atomic_add v2, v9, s[70:71]
	global_atomic_add v2, v9, s[70:71] offset:128
	global_atomic_add v2, v9, s[70:71] offset:256
	global_atomic_add v2, v9, s[70:71] offset:384
	global_atomic_add v2, v9, s[70:71] offset:512
	global_atomic_add v2, v9, s[70:71] offset:640
	global_atomic_add v2, v9, s[70:71] offset:768
	global_atomic_add v2, v9, s[70:71] offset:896
.Lxb3_inv:
	buffer_inv sc1
.Lxb3_poll:
	global_load_dword v10, v8, s[70:71] offset:1024 sc1
	s_add_i32 s10, s10, 1
	s_waitcnt vmcnt(0)
	v_cmp_ge_u32_e32 vcc, v10, v11
	s_cbranch_vccnz .Lxb3_done
	s_sleep 1
	s_cmp_lt_u32 s10, 0x8000
	s_cbranch_scc1 .Lxb3_poll
.Lxb3_done:
.LBB0_349:
	s_or_b64 exec, exec, s[4:5]
	s_add_u32 s40, s70, 0x11d00000
	s_addc_u32 s41, s71, 0
	s_add_u32 s12, s70, 0x12d80000
	s_addc_u32 s13, s71, 0
	s_cmpk_gt_i32 s2, 0x17f
	v_lshrrev_b32_e32 v199, 7, v0
	s_waitcnt lgkmcnt(0)
	s_barrier
	v_readlane_b32 s62, v255, 5
	s_lshr_b32 s63, s62, 2
	s_and_b32 s9, s62, 3
	s_lshr_b32 s73, s2, 6
	s_and_b32 s74, s2, 63
	s_lshl_b32 s74, s74, 5
	s_lshl_b32 s63, s63, 4
	s_add_u32 s74, s74, s63
	s_lshl_b32 s75, s73, 11
	s_add_u32 s75, s75, s74
	s_cmp_eq_u32 s74, 0
	s_cselect_b32 s69, 1, 0
	s_lshl_b32 s93, 2, s9
	s_sub_u32 s93, s93, 1
	s_cmp_eq_u32 s69, 1
	s_cselect_b32 s93, s93, 0
	s_add_u32 s7, s9, 1
	s_lshl_b32 s7, s7, 23
	s_sub_u32 s7, 0x3f800000, s7
	s_mov_b32 s3, 0xffff0000
	s_cmpk_eq_u32 s74, 0x7f0
	s_cselect_b32 s97, 1, 0
	s_lshl_b32 s62, s75, 14
	s_add_u32 s0, s70, s62
	s_addc_u32 s1, s71, 0
	s_add_u32 s0, s0, 0x9900000
	s_addc_u32 s1, s1, 0
	s_lshl_b32 s62, s75, 11
	s_add_u32 s10, s40, s62
	s_addc_u32 s11, s41, 0
	s_add_u32 s32, s12, s62
	s_addc_u32 s33, s13, 0
	s_mul_i32 s62, s73, 0xf000
	s_add_u32 s88, s30, s62
	s_addc_u32 s89, s31, 0
	s_add_u32 s88, s88, 0x4100000
	s_addc_u32 s89, s89, 0
	s_lshl_b32 s62, s73, 13
	s_add_u32 s90, s30, s62
	s_addc_u32 s91, s31, 0
	s_add_u32 s90, s90, 0x413c000
	s_addc_u32 s91, s91, 0
	v_and_b32_e32 v2, 0xff, v0
	v_lshlrev_b32_e32 v4, 4, v2
	v_lshlrev_b32_e32 v2, 3, v2
	v_add_u32_e32 v3, 0x1000, v2
	v_add_u32_e32 v68, 0x1000, v4
	v_add_u32_e32 v69, 0x2000, v4
	v_mov_b32_e32 v38, 0
	v_mov_b32_e32 v39, 0
	v_mov_b32_e32 v40, 0
	v_mov_b32_e32 v41, 0
	v_mov_b32_e32 v42, 0
	v_mov_b32_e32 v43, 0
	v_mov_b32_e32 v44, 0
	v_mov_b32_e32 v45, 0
	v_mov_b32_e32 v46, 0
	v_mov_b32_e32 v47, 0
	v_mov_b32_e32 v48, 0
	v_mov_b32_e32 v49, 0
	v_mov_b32_e32 v50, 0
	v_mov_b32_e32 v51, 0
	v_mov_b32_e32 v52, 0
	v_mov_b32_e32 v53, 0
	v_mov_b32_e32 v54, 0
	v_mov_b32_e32 v55, 0
	v_mov_b32_e32 v56, 0
	v_mov_b32_e32 v57, 0
	v_mov_b32_e32 v58, 0
	v_mov_b32_e32 v59, 0
	v_mov_b32_e32 v60, 0
	v_mov_b32_e32 v61, 0
	v_mov_b32_e32 v62, 0
	v_mov_b32_e32 v63, 0
	v_mov_b32_e32 v64, 0
	v_mov_b32_e32 v65, 0
	v_mov_b32_e32 v66, 0
	v_mov_b32_e32 v67, 0
	v_mov_b32_e32 v212, 0
	v_mov_b32_e32 v213, 0
	v_mov_b32_e32 v214, 0
	v_mov_b32_e32 v215, 0
	v_mov_b32_e32 v216, 0
	v_mov_b32_e32 v217, 0
	v_mov_b32_e32 v218, 0
	v_mov_b32_e32 v219, 0
	s_cmp_eq_u32 s69, 1
	s_cbranch_scc1 .Lp3_hist_done
	s_sub_u32 s4, s0, 0x4000
	s_subb_u32 s5, s1, 0
	global_load_dwordx2 v[38:39], v2, s[4:5]
	global_load_dwordx2 v[212:213], v2, s[4:5] offset:2048
	global_load_dwordx2 v[214:215], v3, s[4:5] offset:2048
	s_sub_u32 s4, s4, 0x4000
	s_subb_u32 s5, s5, 0
	global_load_dwordx2 v[216:217], v2, s[4:5] offset:2048
	global_load_dwordx2 v[218:219], v3, s[4:5] offset:2048
	s_cmp_eq_u32 s9, 0
	s_cbranch_scc1 .Lp3_hist_done
	global_load_dwordx2 v[40:41], v2, s[4:5]
	s_sub_u32 s4, s4, 0x4000
	s_subb_u32 s5, s5, 0
	global_load_dwordx2 v[42:43], v2, s[4:5]
	s_cmp_eq_u32 s9, 1
	s_cbranch_scc1 .Lp3_hist_done
	s_sub_u32 s4, s4, 0x4000
	s_subb_u32 s5, s5, 0
	global_load_dwordx2 v[44:45], v2, s[4:5]
	s_sub_u32 s4, s4, 0x4000
	s_subb_u32 s5, s5, 0
	global_load_dwordx2 v[46:47], v2, s[4:5]
	s_sub_u32 s4, s4, 0x4000
	s_subb_u32 s5, s5, 0
	global_load_dwordx2 v[48:49], v2, s[4:5]
	s_sub_u32 s4, s4, 0x4000
	s_subb_u32 s5, s5, 0
	global_load_dwordx2 v[50:51], v2, s[4:5]
	s_cmp_eq_u32 s9, 2
	s_cbranch_scc1 .Lp3_hist_done
	s_sub_u32 s4, s4, 0x4000
	s_subb_u32 s5, s5, 0
	global_load_dwordx2 v[52:53], v2, s[4:5]
	s_sub_u32 s4, s4, 0x4000
	s_subb_u32 s5, s5, 0
	global_load_dwordx2 v[54:55], v2, s[4:5]
	s_sub_u32 s4, s4, 0x4000
	s_subb_u32 s5, s5, 0
	global_load_dwordx2 v[56:57], v2, s[4:5]
	s_sub_u32 s4, s4, 0x4000
	s_subb_u32 s5, s5, 0
	global_load_dwordx2 v[58:59], v2, s[4:5]
	s_sub_u32 s4, s4, 0x4000
	s_subb_u32 s5, s5, 0
	global_load_dwordx2 v[60:61], v2, s[4:5]
	s_sub_u32 s4, s4, 0x4000
	s_subb_u32 s5, s5, 0
	global_load_dwordx2 v[62:63], v2, s[4:5]
	s_sub_u32 s4, s4, 0x4000
	s_subb_u32 s5, s5, 0
	global_load_dwordx2 v[64:65], v2, s[4:5]
	s_sub_u32 s4, s4, 0x4000
	s_subb_u32 s5, s5, 0
	global_load_dwordx2 v[66:67], v2, s[4:5]

.LBB0_405:
	s_waitcnt vmcnt(0)
	s_barrier
	s_mov_b64 s[4:5], exec
	v_readlane_b32 s0, v255, 3
	v_readlane_b32 s1, v255, 4
	s_and_b64 s[0:1], s[4:5], s[0:1]
	s_mov_b64 exec, s[0:1]
	s_cbranch_execz .LBB0_457
	v_mov_b32_e32 v2, 0x20000
	ds_read_b32 v6, v2
	ds_read_b32 v7, v2 offset:4
	v_readlane_b32 s0, v255, 2
	s_and_b32 s0, s0, 7
	s_lshl_b32 s0, s0, 7
	s_add_i32 s0, s0, 0x3600
	v_mov_b32_e32 v8, s0
	v_mov_b32_e32 v9, 1
	s_mov_b32 s11, 4
	s_mov_b32 s10, 0
	global_atomic_add v10, v8, v9, s[70:71] sc0
	s_waitcnt vmcnt(0) lgkmcnt(0)
	v_mul_lo_u32 v11, v6, s11
	v_add_u32_e32 v10, 1, v10
	v_cmp_eq_u32_e32 vcc, v10, v11
	v_mul_lo_u32 v11, v7, s11
	s_cbranch_vccz .Lxb4_inv
	buffer_wbl2 sc1
	v_mov_b32_e32 v2, 0x3a00
	s_waitcnt vmcnt(0)
	global_atomic_add v2, v9, s[70:71]
	global_atomic_add v2, v9, s[70:71] offset:128
	global_atomic_add v2, v9, s[70:71] offset:256
	global_atomic_add v2, v9, s[70:71] offset:384
	global_atomic_add v2, v9, s[70:71] offset:512
	global_atomic_add v2, v9, s[70:71] offset:640
	global_atomic_add v2, v9, s[70:71] offset:768
	global_atomic_add v2, v9, s[70:71] offset:896
.Lxb4_inv:
	buffer_inv sc1
.Lxb4_poll:
	global_load_dword v10, v8, s[70:71] offset:1024 sc1
	s_add_i32 s10, s10, 1
	s_waitcnt vmcnt(0)
	v_cmp_ge_u32_e32 vcc, v10, v11
	s_cbranch_vccnz .Lxb4_done
	s_sleep 1
	s_cmp_lt_u32 s10, 0x8000
	s_cbranch_scc1 .Lxb4_poll
.Lxb4_done:
.LBB0_457:
	s_or_b64 exec, exec, s[4:5]
	s_cmpk_lt_i32 s2, 0x100
	s_cselect_b64 s[4:5], -1, 0
	s_cmpk_gt_i32 s2, 0xff
	v_readfirstlane_b32 s0, v0
	s_waitcnt lgkmcnt(0)
	s_barrier
	s_cbranch_scc1 .LBB0_463
	s_ashr_i32 s1, s2, 31
	s_lshr_b32 s1, s1, 29
	s_add_i32 s1, s2, s1
	s_and_b32 s3, s1, -8
	s_sub_i32 s3, s2, s3
	s_cmp_gt_i32 s3, -1
	s_cbranch_scc0 .LBB0_460
	s_lshl_b32 s8, s3, 5
	s_cbranch_execz .LBB0_461
	s_branch .LBB0_462

.LBB0_605:
	s_waitcnt vmcnt(0)
	s_barrier
	s_mov_b64 s[4:5], exec
	v_readlane_b32 s0, v255, 3
	v_readlane_b32 s1, v255, 4
	s_and_b64 s[0:1], s[4:5], s[0:1]
	s_mov_b64 exec, s[0:1]
	s_cbranch_execz .LBB0_657
	v_mov_b32_e32 v2, 0x20000
	ds_read_b32 v6, v2
	ds_read_b32 v7, v2 offset:4
	v_readlane_b32 s0, v255, 2
	s_and_b32 s0, s0, 7
	s_lshl_b32 s0, s0, 7
	s_add_i32 s0, s0, 0x3600
	v_mov_b32_e32 v8, s0
	v_mov_b32_e32 v9, 1
	s_mov_b32 s11, 5
	s_mov_b32 s10, 0
	global_atomic_add v10, v8, v9, s[70:71] sc0
	s_waitcnt vmcnt(0) lgkmcnt(0)
	v_mul_lo_u32 v11, v6, s11
	v_add_u32_e32 v10, 1, v10
	v_cmp_eq_u32_e32 vcc, v10, v11
	v_mul_lo_u32 v11, v7, s11
	s_cbranch_vccz .Lxb5_inv
	buffer_wbl2 sc1
	v_mov_b32_e32 v2, 0x3a00
	s_waitcnt vmcnt(0)
	global_atomic_add v2, v9, s[70:71]
	global_atomic_add v2, v9, s[70:71] offset:128
	global_atomic_add v2, v9, s[70:71] offset:256
	global_atomic_add v2, v9, s[70:71] offset:384
	global_atomic_add v2, v9, s[70:71] offset:512
	global_atomic_add v2, v9, s[70:71] offset:640
	global_atomic_add v2, v9, s[70:71] offset:768
	global_atomic_add v2, v9, s[70:71] offset:896
.Lxb5_inv:
	buffer_inv sc1
.Lxb5_poll:
	global_load_dword v10, v8, s[70:71] offset:1024 sc1
	s_add_i32 s10, s10, 1
	s_waitcnt vmcnt(0)
	v_cmp_ge_u32_e32 vcc, v10, v11
	s_cbranch_vccnz .Lxb5_done
	s_sleep 1
	s_cmp_lt_u32 s10, 0x8000
	s_cbranch_scc1 .Lxb5_poll
.Lxb5_done:
.LBB0_657:
	s_or_b64 exec, exec, s[4:5]
	v_bfe_u32 v188, v0, 4, 2
	v_readlane_b32 s0, v255, 18
	v_lshlrev_b32_e32 v189, 4, v188
	v_readlane_b32 s1, v255, 19
	v_readfirstlane_b32 s12, v0
	s_and_b64 vcc, exec, s[0:1]
	v_bitop3_b32 v190, v189, v206, v208 bitop3:0x36
	s_waitcnt lgkmcnt(0)
	s_barrier
	s_cbranch_vccnz .LBB0_681
	s_ashr_i32 s0, s2, 31
	s_lshr_b32 s1, s0, 29
	s_add_i32 s1, s2, s1
	s_and_b32 s3, s1, -8
	s_sub_i32 s6, s2, s3
	s_cmp_gt_i32 s6, -1
	s_cbranch_scc0 .LBB0_660
	s_lshl_b32 s3, s6, 5
	s_cbranch_execz .LBB0_661
	s_branch .LBB0_662

.LBB0_686:
	s_waitcnt vmcnt(0)
	s_waitcnt vmcnt(0)
	s_barrier
	s_mov_b64 s[4:5], exec
	v_readlane_b32 s0, v255, 3
	v_readlane_b32 s1, v255, 4
	s_and_b64 s[0:1], s[4:5], s[0:1]
	s_mov_b64 exec, s[0:1]
	s_cbranch_execz .LBB0_738
	v_mov_b32_e32 v2, 0x20000
	ds_read_b32 v6, v2
	ds_read_b32 v7, v2 offset:4
	v_readlane_b32 s0, v255, 2
	s_and_b32 s0, s0, 7
	s_lshl_b32 s0, s0, 7
	s_add_i32 s0, s0, 0x3600
	v_mov_b32_e32 v8, s0
	v_mov_b32_e32 v9, 1
	s_mov_b32 s11, 6
	s_mov_b32 s10, 0
	global_atomic_add v10, v8, v9, s[70:71] sc0
	s_waitcnt vmcnt(0) lgkmcnt(0)
	v_mul_lo_u32 v11, v6, s11
	v_add_u32_e32 v10, 1, v10
	v_cmp_eq_u32_e32 vcc, v10, v11
	v_mul_lo_u32 v11, v7, s11
	s_cbranch_vccz .Lxb6_inv
	buffer_wbl2 sc1
	v_mov_b32_e32 v2, 0x3a00
	s_waitcnt vmcnt(0)
	global_atomic_add v2, v9, s[70:71]
	global_atomic_add v2, v9, s[70:71] offset:128
	global_atomic_add v2, v9, s[70:71] offset:256
	global_atomic_add v2, v9, s[70:71] offset:384
	global_atomic_add v2, v9, s[70:71] offset:512
	global_atomic_add v2, v9, s[70:71] offset:640
	global_atomic_add v2, v9, s[70:71] offset:768
	global_atomic_add v2, v9, s[70:71] offset:896
.Lxb6_inv:
	buffer_inv sc1
.Lxb6_poll:
	global_load_dword v10, v8, s[70:71] offset:1024 sc1
	s_add_i32 s10, s10, 1
	s_waitcnt vmcnt(0)
	v_cmp_ge_u32_e32 vcc, v10, v11
	s_cbranch_vccnz .Lxb6_done
	s_sleep 1
	s_cmp_lt_u32 s10, 0x8000
	s_cbranch_scc1 .Lxb6_poll
.Lxb6_done:
.LBB0_738:
	s_or_b64 exec, exec, s[4:5]
	v_mov_b32_e32 v95, 0
	v_lshlrev_b32_e32 v94, 4, v170
	v_lshl_add_u64 v[34:35], s[50:51], 0, v[94:95]
	s_movk_i32 s0, 0x1000
	v_add_co_u32_e32 v54, vcc, s0, v34
	v_lshl_add_u64 v[36:37], s[16:17], 0, v[94:95]
	s_nop 0
	v_addc_co_u32_e32 v55, vcc, 0, v35, vcc
	v_add_co_u32_e32 v62, vcc, s0, v36
	s_cmpk_lg_i32 s96, 0x100
	s_nop 0
	v_addc_co_u32_e32 v63, vcc, 0, v37, vcc
	s_cselect_b64 s[12:13], -1, 0
	s_add_i32 s1, s34, 0x207f
	s_and_b32 s3, s68, 15
	s_waitcnt lgkmcnt(0)
	s_barrier
	global_load_dwordx4 v[2:5], v94, s[50:51]
	global_load_dwordx4 v[6:9], v94, s[50:51] offset:1024
	global_load_dwordx4 v[10:13], v94, s[16:17]
	global_load_dwordx4 v[14:17], v94, s[16:17] offset:1024
	global_load_dwordx4 v[18:21], v94, s[50:51] offset:2048
	global_load_dwordx4 v[22:25], v94, s[50:51] offset:3072
	global_load_dwordx4 v[26:29], v94, s[16:17] offset:2048
	global_load_dwordx4 v[30:33], v94, s[16:17] offset:3072
	global_load_dwordx4 v[34:37], v[54:55], off
	global_load_dwordx4 v[38:41], v[54:55], off offset:1024
	global_load_dwordx4 v[42:45], v[62:63], off
	global_load_dwordx4 v[46:49], v[62:63], off offset:1024
	global_load_dwordx4 v[50:53], v[54:55], off offset:2048
	s_nop 0
	global_load_dwordx4 v[54:57], v[54:55], off offset:3072
	s_nop 0
	global_load_dwordx4 v[58:61], v[62:63], off offset:2048
	s_nop 0
	global_load_dwordx4 v[62:65], v[62:63], off offset:3072
	s_cmp_eq_u32 s3, 0
	s_cselect_b64 s[4:5], -1, 0
	s_ashr_i32 s8, s68, 4
	s_cmpk_lt_i32 s8, 0x80
	s_cselect_b64 s[6:7], -1, 0
	s_and_b64 s[4:5], s[4:5], s[6:7]
	s_cmp_eq_u32 s3, 8
	s_cselect_b64 s[6:7], -1, 0
	s_cmpk_lt_i32 s68, 0x808
	s_mul_i32 s3, s96, 24
	s_cselect_b64 s[10:11], -1, 0
	s_add_i32 s3, s3, s68
	s_and_b64 s[6:7], s[10:11], s[6:7]
	s_add_i32 s10, s3, -8
	s_and_b64 s[6:7], s[6:7], exec
	s_cselect_b32 s69, s10, -1
	s_addk_i32 s8, 0x2000
	s_and_b64 s[4:5], s[4:5], exec
	s_cselect_b32 s72, s8, s3
	v_or_b32_e32 v66, 0x1000, v171
	s_mov_b32 s3, 0x5555556
	v_mul_hi_u32 v67, v66, s3
	v_lshl_add_u32 v98, v67, 4, v66
	v_or_b32_e32 v66, 0x1100, v171
	v_mul_hi_u32 v67, v66, s3
	v_lshl_add_u32 v100, v67, 4, v66
	v_or_b32_e32 v66, 0x1200, v171
	v_mul_hi_u32 v67, v66, s3
	v_lshl_add_u32 v102, v67, 4, v66
	v_or_b32_e32 v66, 0x1300, v171
	v_mul_hi_u32 v67, v66, s3
	v_lshl_add_u32 v104, v67, 4, v66
	v_or_b32_e32 v66, 0x1400, v171
	v_mul_hi_u32 v67, v66, s3
	v_lshl_add_u32 v106, v67, 4, v66
	v_or_b32_e32 v66, 0x1500, v171
	v_mul_hi_u32 v67, v66, s3
	v_lshl_add_u32 v108, v67, 4, v66
	v_or_b32_e32 v66, 0x1600, v171
	v_mul_hi_u32 v67, v66, s3
	v_lshl_add_u32 v110, v67, 4, v66
	v_or_b32_e32 v66, 0x1700, v171
	v_mul_hi_u32 v67, v66, s3
	v_lshl_add_u32 v112, v67, 4, v66
	v_or_b32_e32 v66, 0x2000, v171
	v_mul_hi_u32 v67, v66, s3
	v_lshl_add_u32 v116, v67, 4, v66
	v_or_b32_e32 v66, 0x1800, v171
	v_mul_hi_u32 v67, v66, s3
	v_lshl_add_u32 v118, v67, 4, v66
	v_or_b32_e32 v66, 0x2100, v171
	v_mul_hi_u32 v67, v66, s3
	v_lshl_add_u32 v120, v67, 4, v66
	v_or_b32_e32 v66, 0x1900, v171
	v_mul_hi_u32 v67, v66, s3
	v_lshl_add_u32 v122, v67, 4, v66
	v_or_b32_e32 v66, 0x2200, v171
	v_mul_hi_u32 v67, v66, s3
	v_lshl_add_u32 v124, v67, 4, v66
	v_or_b32_e32 v66, 0x1a00, v171
	v_mul_hi_u32 v67, v66, s3
	v_lshl_add_u32 v126, v67, 4, v66
	v_or_b32_e32 v66, 0x2300, v171
	v_mul_hi_u32 v67, v66, s3
	v_lshl_add_u32 v128, v67, 4, v66
	v_or_b32_e32 v66, 0x1b00, v171
	v_mul_hi_u32 v67, v66, s3
	v_lshl_add_u32 v130, v67, 4, v66
	v_or_b32_e32 v66, 0x2400, v171
	v_mul_hi_u32 v67, v66, s3
	v_lshl_add_u32 v132, v67, 4, v66
	v_or_b32_e32 v66, 0x1c00, v171
	v_mul_hi_u32 v67, v66, s3
	v_lshl_add_u32 v134, v67, 4, v66
	v_or_b32_e32 v66, 0x2500, v171
	v_mul_hi_u32 v67, v66, s3
	v_lshl_add_u32 v136, v67, 4, v66
	v_or_b32_e32 v66, 0x1d00, v171
	v_mul_hi_u32 v67, v66, s3
	v_lshl_add_u32 v138, v67, 4, v66
	v_or_b32_e32 v66, 0x2600, v171
	v_lshl_add_u64 v[174:175], s[42:43], 0, v[94:95]
	s_mov_b64 s[4:5], 0x1000
	v_mul_hi_u32 v67, v66, s3
	v_lshl_add_u64 v[176:177], v[174:175], 0, s[4:5]
	s_mov_b64 s[4:5], 0x1400
	v_lshl_add_u32 v140, v67, 4, v66
	v_or_b32_e32 v66, 0x1e00, v171
	v_lshl_add_u64 v[178:179], v[174:175], 0, s[4:5]
	s_mov_b64 s[4:5], 0x1800
	v_mul_hi_u32 v67, v66, s3
	v_lshl_add_u64 v[180:181], v[174:175], 0, s[4:5]
	s_mov_b64 s[4:5], 0x1c00
	v_lshl_add_u32 v142, v67, 4, v66
	v_or_b32_e32 v66, 0x2700, v171
	v_lshl_add_u64 v[182:183], v[174:175], 0, s[4:5]
	v_mul_hi_u32 v67, v66, s3
	s_abs_i32 s4, s34
	v_lshl_add_u32 v144, v67, 4, v66
	v_cvt_f32_u32_e32 v66, s4
	s_sub_i32 s5, 0, s4
	v_or_b32_e32 v67, 0x1f00, v171
	v_mul_hi_u32 v68, v67, s3
	v_rcp_iflag_f32_e32 v66, v66
	s_xor_b32 s3, s1, s34
	s_abs_i32 s1, s1
	s_ashr_i32 s3, s3, 31
	v_mul_f32_e32 v66, 0x4f7ffffe, v66
	v_cvt_u32_f32_e32 v66, v66
	v_mov_b32_e32 v159, v95
	s_mov_b32 s9, 0
	v_lshl_add_u64 v[96:97], s[44:45], 0, v[158:159]
	v_readfirstlane_b32 s6, v66
	s_mul_i32 s5, s5, s6
	s_mul_hi_u32 s5, s6, s5
	s_add_i32 s6, s6, s5
	s_mul_hi_u32 s5, s1, s6
	s_mul_i32 s6, s5, s4
	s_sub_i32 s1, s1, s6
	s_add_i32 s6, s5, 1
	s_sub_i32 s7, s1, s4
	s_cmp_ge_u32 s1, s4
	s_cselect_b32 s5, s6, s5
	s_cselect_b32 s1, s7, s1
	s_add_i32 s6, s5, 1
	s_cmp_ge_u32 s1, s4
	s_cselect_b32 s1, s6, s5
	s_xor_b32 s1, s1, s3
	v_mbcnt_lo_u32_b32 v66, -1, 0
	v_lshl_add_u64 v[172:173], s[40:41], 0, v[94:95]
	v_mov_b32_e32 v99, v95
	v_mov_b32_e32 v101, v95
	v_mov_b32_e32 v103, v95
	v_mov_b32_e32 v105, v95
	v_mov_b32_e32 v107, v95
	v_mov_b32_e32 v109, v95
	v_mov_b32_e32 v111, v95
	v_mov_b32_e32 v113, v95
	v_lshl_add_u64 v[114:115], s[54:55], 0, v[94:95]
	v_mov_b32_e32 v117, v95
	v_mov_b32_e32 v119, v95
	v_mov_b32_e32 v121, v95
	v_mov_b32_e32 v123, v95
	v_mov_b32_e32 v125, v95
	v_mov_b32_e32 v127, v95
	v_mov_b32_e32 v129, v95
	v_mov_b32_e32 v131, v95
	v_mov_b32_e32 v133, v95
	v_mov_b32_e32 v135, v95
	v_mov_b32_e32 v137, v95
	v_mov_b32_e32 v139, v95
	v_mov_b32_e32 v141, v95
	v_mov_b32_e32 v143, v95
	v_mov_b32_e32 v145, v95
	v_lshl_add_u32 v146, v68, 4, v67
	v_mov_b32_e32 v147, v95
	s_sub_i32 s73, s1, s3
	s_mov_b32 s1, 0x100000
	s_mov_b32 s3, 0x200000
	s_mov_b32 s10, 0x300000
	s_mov_b32 s11, 0x400000
	s_mov_b32 s17, 0x500000
	s_mov_b32 s50, 0x600000
	s_mov_b32 s51, 0x700000
	s_mov_b32 s16, 0x3f9837f0
	v_mov_b32_e32 v151, 0x3727c5ac
	s_mov_b32 s54, 0xf800000
	v_mov_b32_e32 v153, 0x260
	s_movk_i32 s55, 0x7fff
	s_mov_b32 s56, 0xffff0000
	v_mov_b32_e32 v155, 0x2000
	v_mov_b32_e32 v157, 0x207f
	v_mbcnt_hi_u32_b32 v211, -1, v66
	s_mov_b32 s57, s68
	s_mov_b32 s58, s68
	s_mov_b32 s59, 0
	v_cndmask_b32_e64 v66, 0, 1, s[12:13]
	v_cmp_ne_u32_e64 s[4:5], 1, v66
	s_mov_b32 s3, 0x3f9837f0
	v_lshlrev_b32_e32 v129, 4, v170
	v_add_u32_e32 v131, 0x1000, v129
	v_lshlrev_b32_e32 v117, 3, v170
	v_xor_b32_e32 v99, 1, v211
	v_lshlrev_b32_e32 v99, 2, v99
	v_xor_b32_e32 v101, 2, v211
	v_lshlrev_b32_e32 v101, 2, v101
	v_xor_b32_e32 v103, 4, v211
	v_lshlrev_b32_e32 v103, 2, v103
	v_xor_b32_e32 v105, 8, v211
	v_lshlrev_b32_e32 v105, 2, v105
	v_xor_b32_e32 v107, 16, v211
	v_lshlrev_b32_e32 v107, 2, v107
	v_xor_b32_e32 v119, 32, v211
	v_lshlrev_b32_e32 v119, 2, v119
	s_mov_b32 s0, s68
	s_lshl_b32 s1, s0, 13
	s_add_u32 s6, s40, s1
	s_addc_u32 s7, s41, 0
	s_lshl_b32 s1, s0, 12
	s_add_u32 s10, s44, s1
	s_addc_u32 s11, s45, 0
	s_lshr_b32 s1, s0, 11
	s_lshl_b32 s1, s1, 16
	s_add_u32 s16, s14, s1
	s_addc_u32 s17, s15, 0
	global_load_dwordx4 v[66:69], v129, s[6:7]
	global_load_dwordx4 v[70:73], v129, s[6:7] offset:1024
	global_load_dwordx4 v[74:77], v129, s[6:7] offset:2048
	global_load_dwordx4 v[78:81], v129, s[6:7] offset:3072
	global_load_dwordx4 v[82:85], v131, s[6:7]
	global_load_dwordx4 v[86:89], v131, s[6:7] offset:1024
	global_load_dwordx4 v[90:93], v131, s[6:7] offset:2048
	global_load_dwordx4 v[94:97], v131, s[6:7] offset:3072
	v_lshlrev_b32_e32 v151, 2, v116
	global_load_dwordx4 v[158:161], v151, s[16:17]
	v_lshlrev_b32_e32 v151, 2, v118
	global_load_dwordx4 v[220:223], v151, s[16:17]
	v_lshlrev_b32_e32 v151, 2, v120
	global_load_dwordx4 v[162:165], v151, s[16:17]
	v_lshlrev_b32_e32 v151, 2, v122
	global_load_dwordx4 v[224:227], v151, s[16:17]
	v_lshlrev_b32_e32 v151, 2, v124
	global_load_dwordx4 v[166:169], v151, s[16:17]
	v_lshlrev_b32_e32 v151, 2, v126
	global_load_dwordx4 v[228:231], v151, s[16:17]
	v_lshlrev_b32_e32 v151, 2, v128
	global_load_dwordx4 v[176:179], v151, s[16:17]
	v_lshlrev_b32_e32 v151, 2, v130
	global_load_dwordx4 v[232:235], v151, s[16:17]
	v_lshlrev_b32_e32 v151, 2, v132
	global_load_dwordx4 v[180:183], v151, s[16:17]
	v_lshlrev_b32_e32 v151, 2, v134
	global_load_dwordx4 v[236:239], v151, s[16:17]
	v_lshlrev_b32_e32 v151, 2, v136
	global_load_dwordx4 v[184:187], v151, s[16:17]
	v_lshlrev_b32_e32 v151, 2, v138
	global_load_dwordx4 v[240:243], v151, s[16:17]
	v_lshlrev_b32_e32 v151, 2, v140
	global_load_dwordx4 v[212:215], v151, s[16:17]
	v_lshlrev_b32_e32 v151, 2, v142
	global_load_dwordx4 v[244:247], v151, s[16:17]
	v_lshlrev_b32_e32 v151, 2, v144
	global_load_dwordx4 v[216:219], v151, s[16:17]
	v_lshlrev_b32_e32 v151, 2, v146
	global_load_dwordx4 v[248:251], v151, s[16:17]
	s_waitcnt vmcnt(23)
	v_add_f32_e32 v151, v66, v67
	v_add_f32_e32 v155, v68, v69
	v_add_f32_e32 v151, v151, v155
	v_add_f32_e32 v153, 0, v151
	s_waitcnt vmcnt(22)
	v_add_f32_e32 v151, v70, v71
	v_add_f32_e32 v155, v72, v73
	v_add_f32_e32 v151, v151, v155
	v_add_f32_e32 v153, v153, v151
	s_waitcnt vmcnt(21)
	v_add_f32_e32 v151, v74, v75
	v_add_f32_e32 v155, v76, v77
	v_add_f32_e32 v151, v151, v155
	v_add_f32_e32 v153, v153, v151
	s_waitcnt vmcnt(20)
	v_add_f32_e32 v151, v78, v79
	v_add_f32_e32 v155, v80, v81
	v_add_f32_e32 v151, v151, v155
	v_add_f32_e32 v153, v153, v151
	s_waitcnt vmcnt(19)
	v_add_f32_e32 v151, v82, v83
	v_add_f32_e32 v155, v84, v85
	v_add_f32_e32 v151, v151, v155
	v_add_f32_e32 v153, v153, v151
	s_waitcnt vmcnt(18)
	v_add_f32_e32 v151, v86, v87
	v_add_f32_e32 v155, v88, v89
	v_add_f32_e32 v151, v151, v155
	v_add_f32_e32 v153, v153, v151
	s_waitcnt vmcnt(17)
	v_add_f32_e32 v151, v90, v91
	v_add_f32_e32 v155, v92, v93
	v_add_f32_e32 v151, v151, v155
	v_add_f32_e32 v153, v153, v151
	s_waitcnt vmcnt(16)
	v_add_f32_e32 v151, v94, v95
	v_add_f32_e32 v155, v96, v97
	v_add_f32_e32 v151, v151, v155
	v_add_f32_e32 v153, v153, v151
	ds_bpermute_b32 v151, v99, v153
	s_waitcnt lgkmcnt(0)
	v_add_f32_e32 v153, v153, v151
	ds_bpermute_b32 v151, v101, v153
	s_waitcnt lgkmcnt(0)
	v_add_f32_e32 v153, v153, v151
	ds_bpermute_b32 v151, v103, v153
	s_waitcnt lgkmcnt(0)
	v_add_f32_e32 v153, v153, v151
	ds_bpermute_b32 v151, v105, v153
	s_waitcnt lgkmcnt(0)
	v_add_f32_e32 v153, v153, v151
	ds_bpermute_b32 v151, v107, v153
	s_waitcnt lgkmcnt(0)
	v_add_f32_e32 v153, v153, v151
	ds_bpermute_b32 v151, v119, v153
	s_waitcnt lgkmcnt(0)
	v_add_f32_e32 v153, v153, v151
	v_fmac_f32_e32 v66, 0xba000000, v153
	v_fmac_f32_e32 v67, 0xba000000, v153
	v_fmac_f32_e32 v68, 0xba000000, v153
	v_fmac_f32_e32 v69, 0xba000000, v153
	v_fmac_f32_e32 v70, 0xba000000, v153
	v_fmac_f32_e32 v71, 0xba000000, v153
	v_fmac_f32_e32 v72, 0xba000000, v153
	v_fmac_f32_e32 v73, 0xba000000, v153
	v_fmac_f32_e32 v74, 0xba000000, v153
	v_fmac_f32_e32 v75, 0xba000000, v153
	v_fmac_f32_e32 v76, 0xba000000, v153
	v_fmac_f32_e32 v77, 0xba000000, v153
	v_fmac_f32_e32 v78, 0xba000000, v153
	v_fmac_f32_e32 v79, 0xba000000, v153
	v_fmac_f32_e32 v80, 0xba000000, v153
	v_fmac_f32_e32 v81, 0xba000000, v153
	v_fmac_f32_e32 v82, 0xba000000, v153
	v_fmac_f32_e32 v83, 0xba000000, v153
	v_fmac_f32_e32 v84, 0xba000000, v153
	v_fmac_f32_e32 v85, 0xba000000, v153
	v_fmac_f32_e32 v86, 0xba000000, v153
	v_fmac_f32_e32 v87, 0xba000000, v153
	v_fmac_f32_e32 v88, 0xba000000, v153
	v_fmac_f32_e32 v89, 0xba000000, v153
	v_fmac_f32_e32 v90, 0xba000000, v153
	v_fmac_f32_e32 v91, 0xba000000, v153
	v_fmac_f32_e32 v92, 0xba000000, v153
	v_fmac_f32_e32 v93, 0xba000000, v153
	v_fmac_f32_e32 v94, 0xba000000, v153
	v_fmac_f32_e32 v95, 0xba000000, v153
	v_fmac_f32_e32 v96, 0xba000000, v153
	v_fmac_f32_e32 v97, 0xba000000, v153
	v_mul_f32_e32 v151, v67, v67
	v_fma_f32 v151, v66, v66, v151
	v_mul_f32_e32 v155, v69, v69
	v_fma_f32 v155, v68, v68, v155
	v_add_f32_e32 v151, v151, v155
	v_add_f32_e32 v157, 0, v151
	v_mul_f32_e32 v151, v71, v71
	v_fma_f32 v151, v70, v70, v151
	v_mul_f32_e32 v155, v73, v73
	v_fma_f32 v155, v72, v72, v155
	v_add_f32_e32 v151, v151, v155
	v_add_f32_e32 v157, v157, v151
	v_mul_f32_e32 v151, v75, v75
	v_fma_f32 v151, v74, v74, v151
	v_mul_f32_e32 v155, v77, v77
	v_fma_f32 v155, v76, v76, v155
	v_add_f32_e32 v151, v151, v155
	v_add_f32_e32 v157, v157, v151
	v_mul_f32_e32 v151, v79, v79
	v_fma_f32 v151, v78, v78, v151
	v_mul_f32_e32 v155, v81, v81
	v_fma_f32 v155, v80, v80, v155
	v_add_f32_e32 v151, v151, v155
	v_add_f32_e32 v157, v157, v151
	v_mul_f32_e32 v151, v83, v83
	v_fma_f32 v151, v82, v82, v151
	v_mul_f32_e32 v155, v85, v85
	v_fma_f32 v155, v84, v84, v155
	v_add_f32_e32 v151, v151, v155
	v_add_f32_e32 v157, v157, v151
	v_mul_f32_e32 v151, v87, v87
	v_fma_f32 v151, v86, v86, v151
	v_mul_f32_e32 v155, v89, v89
	v_fma_f32 v155, v88, v88, v155
	v_add_f32_e32 v151, v151, v155
	v_add_f32_e32 v157, v157, v151
	v_mul_f32_e32 v151, v91, v91
	v_fma_f32 v151, v90, v90, v151
	v_mul_f32_e32 v155, v93, v93
	v_fma_f32 v155, v92, v92, v155
	v_add_f32_e32 v151, v151, v155
	v_add_f32_e32 v157, v157, v151
	v_mul_f32_e32 v151, v95, v95
	v_fma_f32 v151, v94, v94, v151
	v_mul_f32_e32 v155, v97, v97
	v_fma_f32 v155, v96, v96, v155
	v_add_f32_e32 v151, v151, v155
	v_add_f32_e32 v157, v157, v151
	ds_bpermute_b32 v151, v99, v157
	s_waitcnt lgkmcnt(0)
	v_add_f32_e32 v157, v157, v151
	ds_bpermute_b32 v151, v101, v157
	s_waitcnt lgkmcnt(0)
	v_add_f32_e32 v157, v157, v151
	ds_bpermute_b32 v151, v103, v157
	s_waitcnt lgkmcnt(0)
	v_add_f32_e32 v157, v157, v151
	ds_bpermute_b32 v151, v105, v157
	s_waitcnt lgkmcnt(0)
	v_add_f32_e32 v157, v157, v151
	ds_bpermute_b32 v151, v107, v157
	s_waitcnt lgkmcnt(0)
	v_add_f32_e32 v157, v157, v151
	ds_bpermute_b32 v151, v119, v157
	s_waitcnt lgkmcnt(0)
	v_add_f32_e32 v157, v157, v151
	v_mov_b32_e32 v254, 0x3727c5ac
	v_fmamk_f32 v157, v157, 0x3a000000, v254
	v_mul_f32_e32 v151, 0x4f800000, v157
	s_mov_b32 s9, 0xf800000
	v_cmp_gt_f32_e32 vcc, s9, v157
	s_nop 1
	v_cndmask_b32_e32 v157, v157, v151, vcc
	v_sqrt_f32_e32 v151, v157
	s_nop 0
	v_add_u32_e32 v203, -1, v151
	v_fma_f32 v204, -v203, v151, v157
	v_cmp_ge_f32_e64 s[88:89], 0, v204
	v_add_u32_e32 v204, 1, v151
	s_nop 0
	v_cndmask_b32_e64 v203, v151, v203, s[88:89]
	v_fma_f32 v151, -v204, v151, v157
	v_cmp_lt_f32_e64 s[88:89], 0, v151
	s_nop 1
	v_cndmask_b32_e64 v151, v203, v204, s[88:89]
	v_mul_f32_e32 v203, 0x37800000, v151
	v_cndmask_b32_e32 v151, v151, v203, vcc
	v_mov_b32_e32 v203, 0x260
	v_cmp_class_f32_e32 vcc, v157, v203
	s_nop 1
	v_cndmask_b32_e32 v157, v151, v157, vcc
	v_div_scale_f32 v151, s[88:89], v157, v157, 1.0
	v_rcp_f32_e32 v203, v151
	s_nop 0
	v_fma_f32 v204, -v151, v203, 1.0
	v_fmac_f32_e32 v203, v204, v203
	v_div_scale_f32 v204, vcc, 1.0, v157, 1.0
	v_mul_f32_e32 v205, v204, v203
	v_fma_f32 v254, -v151, v205, v204
	v_fmac_f32_e32 v205, v254, v203
	v_fma_f32 v151, -v151, v205, v204
	v_div_fmas_f32 v151, v151, v203, v205
	v_div_fixup_f32 v155, v151, v157, 1.0
	v_mul_f32_e32 v66, v66, v155
	v_mul_f32_e32 v67, v67, v155
	v_mul_f32_e32 v68, v68, v155
	v_mul_f32_e32 v69, v69, v155
	v_pk_fma_f32 v[66:67], v[2:3], v[66:67], v[10:11]
	v_pk_fma_f32 v[68:69], v[4:5], v[68:69], v[12:13]
	global_store_dwordx4 v129, v[66:69], s[6:7]
	s_waitcnt vmcnt(15)
	v_pk_add_f32 v[158:159], v[158:159], 1.0 op_sel_hi:[1,0]
	v_pk_add_f32 v[160:161], v[160:161], 1.0 op_sel_hi:[1,0]
	v_pk_fma_f32 v[158:159], v[158:159], v[66:67], v[220:221]
	v_pk_fma_f32 v[160:161], v[160:161], v[68:69], v[222:223]
	v_cvt_pk_bf16_f32 v158, v158, v159
	v_cvt_pk_bf16_f32 v159, v160, v161
	global_store_dwordx2 v117, v[158:159], s[10:11]
	v_mul_f32_e32 v70, v70, v155
	v_mul_f32_e32 v71, v71, v155
	v_mul_f32_e32 v72, v72, v155
	v_mul_f32_e32 v73, v73, v155
	v_pk_fma_f32 v[70:71], v[6:7], v[70:71], v[14:15]
	v_pk_fma_f32 v[72:73], v[8:9], v[72:73], v[16:17]
	global_store_dwordx4 v129, v[70:73], s[6:7] offset:1024
	s_waitcnt vmcnt(15)
	v_pk_add_f32 v[162:163], v[162:163], 1.0 op_sel_hi:[1,0]
	v_pk_add_f32 v[164:165], v[164:165], 1.0 op_sel_hi:[1,0]
	v_pk_fma_f32 v[162:163], v[162:163], v[70:71], v[224:225]
	v_pk_fma_f32 v[164:165], v[164:165], v[72:73], v[226:227]
	v_cvt_pk_bf16_f32 v162, v162, v163
	v_cvt_pk_bf16_f32 v163, v164, v165
	global_store_dwordx2 v117, v[162:163], s[10:11] offset:512
	v_mul_f32_e32 v74, v74, v155
	v_mul_f32_e32 v75, v75, v155
	v_mul_f32_e32 v76, v76, v155
	v_mul_f32_e32 v77, v77, v155
	v_pk_fma_f32 v[74:75], v[18:19], v[74:75], v[26:27]
	v_pk_fma_f32 v[76:77], v[20:21], v[76:77], v[28:29]
	global_store_dwordx4 v129, v[74:77], s[6:7] offset:2048
	s_waitcnt vmcnt(15)
	v_pk_add_f32 v[166:167], v[166:167], 1.0 op_sel_hi:[1,0]
	v_pk_add_f32 v[168:169], v[168:169], 1.0 op_sel_hi:[1,0]
	v_pk_fma_f32 v[166:167], v[166:167], v[74:75], v[228:229]
	v_pk_fma_f32 v[168:169], v[168:169], v[76:77], v[230:231]
	v_cvt_pk_bf16_f32 v166, v166, v167
	v_cvt_pk_bf16_f32 v167, v168, v169
	global_store_dwordx2 v117, v[166:167], s[10:11] offset:1024
	v_mul_f32_e32 v78, v78, v155
	v_mul_f32_e32 v79, v79, v155
	v_mul_f32_e32 v80, v80, v155
	v_mul_f32_e32 v81, v81, v155
	v_pk_fma_f32 v[78:79], v[22:23], v[78:79], v[30:31]
	v_pk_fma_f32 v[80:81], v[24:25], v[80:81], v[32:33]
	global_store_dwordx4 v129, v[78:81], s[6:7] offset:3072
	s_waitcnt vmcnt(15)
	v_pk_add_f32 v[176:177], v[176:177], 1.0 op_sel_hi:[1,0]
	v_pk_add_f32 v[178:179], v[178:179], 1.0 op_sel_hi:[1,0]
	v_pk_fma_f32 v[176:177], v[176:177], v[78:79], v[232:233]
	v_pk_fma_f32 v[178:179], v[178:179], v[80:81], v[234:235]
	v_cvt_pk_bf16_f32 v176, v176, v177
	v_cvt_pk_bf16_f32 v177, v178, v179
	global_store_dwordx2 v117, v[176:177], s[10:11] offset:1536
	v_mul_f32_e32 v82, v82, v155
	v_mul_f32_e32 v83, v83, v155
	v_mul_f32_e32 v84, v84, v155
	v_mul_f32_e32 v85, v85, v155
	v_pk_fma_f32 v[82:83], v[34:35], v[82:83], v[42:43]
	v_pk_fma_f32 v[84:85], v[36:37], v[84:85], v[44:45]
	global_store_dwordx4 v131, v[82:85], s[6:7]
	s_waitcnt vmcnt(15)
	v_pk_add_f32 v[180:181], v[180:181], 1.0 op_sel_hi:[1,0]
	v_pk_add_f32 v[182:183], v[182:183], 1.0 op_sel_hi:[1,0]
	v_pk_fma_f32 v[180:181], v[180:181], v[82:83], v[236:237]
	v_pk_fma_f32 v[182:183], v[182:183], v[84:85], v[238:239]
	v_cvt_pk_bf16_f32 v180, v180, v181
	v_cvt_pk_bf16_f32 v181, v182, v183
	global_store_dwordx2 v117, v[180:181], s[10:11] offset:2048
	v_mul_f32_e32 v86, v86, v155
	v_mul_f32_e32 v87, v87, v155
	v_mul_f32_e32 v88, v88, v155
	v_mul_f32_e32 v89, v89, v155
	v_pk_fma_f32 v[86:87], v[38:39], v[86:87], v[46:47]
	v_pk_fma_f32 v[88:89], v[40:41], v[88:89], v[48:49]
	global_store_dwordx4 v131, v[86:89], s[6:7] offset:1024
	s_waitcnt vmcnt(15)
	v_pk_add_f32 v[184:185], v[184:185], 1.0 op_sel_hi:[1,0]
	v_pk_add_f32 v[186:187], v[186:187], 1.0 op_sel_hi:[1,0]
	v_pk_fma_f32 v[184:185], v[184:185], v[86:87], v[240:241]
	v_pk_fma_f32 v[186:187], v[186:187], v[88:89], v[242:243]
	v_cvt_pk_bf16_f32 v184, v184, v185
	v_cvt_pk_bf16_f32 v185, v186, v187
	global_store_dwordx2 v117, v[184:185], s[10:11] offset:2560
	v_mul_f32_e32 v90, v90, v155
	v_mul_f32_e32 v91, v91, v155
	v_mul_f32_e32 v92, v92, v155
	v_mul_f32_e32 v93, v93, v155
	v_pk_fma_f32 v[90:91], v[50:51], v[90:91], v[58:59]
	v_pk_fma_f32 v[92:93], v[52:53], v[92:93], v[60:61]
	global_store_dwordx4 v131, v[90:93], s[6:7] offset:2048
	s_waitcnt vmcnt(15)
	v_pk_add_f32 v[212:213], v[212:213], 1.0 op_sel_hi:[1,0]
	v_pk_add_f32 v[214:215], v[214:215], 1.0 op_sel_hi:[1,0]
	v_pk_fma_f32 v[212:213], v[212:213], v[90:91], v[244:245]
	v_pk_fma_f32 v[214:215], v[214:215], v[92:93], v[246:247]
	v_cvt_pk_bf16_f32 v212, v212, v213
	v_cvt_pk_bf16_f32 v213, v214, v215
	global_store_dwordx2 v117, v[212:213], s[10:11] offset:3072
	v_mul_f32_e32 v94, v94, v155
	v_mul_f32_e32 v95, v95, v155
	v_mul_f32_e32 v96, v96, v155
	v_mul_f32_e32 v97, v97, v155
	v_pk_fma_f32 v[94:95], v[54:55], v[94:95], v[62:63]
	v_pk_fma_f32 v[96:97], v[56:57], v[96:97], v[64:65]
	global_store_dwordx4 v131, v[94:97], s[6:7] offset:3072
	s_waitcnt vmcnt(15)
	v_pk_add_f32 v[216:217], v[216:217], 1.0 op_sel_hi:[1,0]
	v_pk_add_f32 v[218:219], v[218:219], 1.0 op_sel_hi:[1,0]
	v_pk_fma_f32 v[216:217], v[216:217], v[94:95], v[248:249]
	v_pk_fma_f32 v[218:219], v[218:219], v[96:97], v[250:251]
	v_cvt_pk_bf16_f32 v216, v216, v217
	v_cvt_pk_bf16_f32 v217, v218, v219
	global_store_dwordx2 v117, v[216:217], s[10:11] offset:3584
	s_add_i32 s0, s68, 0x800
	s_lshl_b32 s1, s0, 13
	s_add_u32 s6, s40, s1
	s_addc_u32 s7, s41, 0
	s_lshl_b32 s1, s0, 12
	s_add_u32 s10, s44, s1
	s_addc_u32 s11, s45, 0
	s_lshr_b32 s1, s0, 11
	s_lshl_b32 s1, s1, 16
	s_add_u32 s16, s14, s1
	s_addc_u32 s17, s15, 0
	global_load_dwordx4 v[66:69], v129, s[6:7]
	global_load_dwordx4 v[70:73], v129, s[6:7] offset:1024
	global_load_dwordx4 v[74:77], v129, s[6:7] offset:2048
	global_load_dwordx4 v[78:81], v129, s[6:7] offset:3072
	global_load_dwordx4 v[82:85], v131, s[6:7]
	global_load_dwordx4 v[86:89], v131, s[6:7] offset:1024
	global_load_dwordx4 v[90:93], v131, s[6:7] offset:2048
	global_load_dwordx4 v[94:97], v131, s[6:7] offset:3072
	v_lshlrev_b32_e32 v151, 2, v116
	global_load_dwordx4 v[158:161], v151, s[16:17]
	v_lshlrev_b32_e32 v151, 2, v118
	global_load_dwordx4 v[220:223], v151, s[16:17]
	v_lshlrev_b32_e32 v151, 2, v120
	global_load_dwordx4 v[162:165], v151, s[16:17]
	v_lshlrev_b32_e32 v151, 2, v122
	global_load_dwordx4 v[224:227], v151, s[16:17]
	v_lshlrev_b32_e32 v151, 2, v124
	global_load_dwordx4 v[166:169], v151, s[16:17]
	v_lshlrev_b32_e32 v151, 2, v126
	global_load_dwordx4 v[228:231], v151, s[16:17]
	v_lshlrev_b32_e32 v151, 2, v128
	global_load_dwordx4 v[176:179], v151, s[16:17]
	v_lshlrev_b32_e32 v151, 2, v130
	global_load_dwordx4 v[232:235], v151, s[16:17]
	v_lshlrev_b32_e32 v151, 2, v132
	global_load_dwordx4 v[180:183], v151, s[16:17]
	v_lshlrev_b32_e32 v151, 2, v134
	global_load_dwordx4 v[236:239], v151, s[16:17]
	v_lshlrev_b32_e32 v151, 2, v136
	global_load_dwordx4 v[184:187], v151, s[16:17]
	v_lshlrev_b32_e32 v151, 2, v138
	global_load_dwordx4 v[240:243], v151, s[16:17]
	v_lshlrev_b32_e32 v151, 2, v140
	global_load_dwordx4 v[212:215], v151, s[16:17]
	v_lshlrev_b32_e32 v151, 2, v142
	global_load_dwordx4 v[244:247], v151, s[16:17]
	v_lshlrev_b32_e32 v151, 2, v144
	global_load_dwordx4 v[216:219], v151, s[16:17]
	v_lshlrev_b32_e32 v151, 2, v146
	global_load_dwordx4 v[248:251], v151, s[16:17]
	s_waitcnt vmcnt(23)
	v_add_f32_e32 v151, v66, v67
	v_add_f32_e32 v155, v68, v69
	v_add_f32_e32 v151, v151, v155
	v_add_f32_e32 v153, 0, v151
	s_waitcnt vmcnt(22)
	v_add_f32_e32 v151, v70, v71
	v_add_f32_e32 v155, v72, v73
	v_add_f32_e32 v151, v151, v155
	v_add_f32_e32 v153, v153, v151
	s_waitcnt vmcnt(21)
	v_add_f32_e32 v151, v74, v75
	v_add_f32_e32 v155, v76, v77
	v_add_f32_e32 v151, v151, v155
	v_add_f32_e32 v153, v153, v151
	s_waitcnt vmcnt(20)
	v_add_f32_e32 v151, v78, v79
	v_add_f32_e32 v155, v80, v81
	v_add_f32_e32 v151, v151, v155
	v_add_f32_e32 v153, v153, v151
	s_waitcnt vmcnt(19)
	v_add_f32_e32 v151, v82, v83
	v_add_f32_e32 v155, v84, v85
	v_add_f32_e32 v151, v151, v155
	v_add_f32_e32 v153, v153, v151
	s_waitcnt vmcnt(18)
	v_add_f32_e32 v151, v86, v87
	v_add_f32_e32 v155, v88, v89
	v_add_f32_e32 v151, v151, v155
	v_add_f32_e32 v153, v153, v151
	s_waitcnt vmcnt(17)
	v_add_f32_e32 v151, v90, v91
	v_add_f32_e32 v155, v92, v93
	v_add_f32_e32 v151, v151, v155
	v_add_f32_e32 v153, v153, v151
	s_waitcnt vmcnt(16)
	v_add_f32_e32 v151, v94, v95
	v_add_f32_e32 v155, v96, v97
	v_add_f32_e32 v151, v151, v155
	v_add_f32_e32 v153, v153, v151
	ds_bpermute_b32 v151, v99, v153
	s_waitcnt lgkmcnt(0)
	v_add_f32_e32 v153, v153, v151
	ds_bpermute_b32 v151, v101, v153
	s_waitcnt lgkmcnt(0)
	v_add_f32_e32 v153, v153, v151
	ds_bpermute_b32 v151, v103, v153
	s_waitcnt lgkmcnt(0)
	v_add_f32_e32 v153, v153, v151
	ds_bpermute_b32 v151, v105, v153
	s_waitcnt lgkmcnt(0)
	v_add_f32_e32 v153, v153, v151
	ds_bpermute_b32 v151, v107, v153
	s_waitcnt lgkmcnt(0)
	v_add_f32_e32 v153, v153, v151
	ds_bpermute_b32 v151, v119, v153
	s_waitcnt lgkmcnt(0)
	v_add_f32_e32 v153, v153, v151
	v_fmac_f32_e32 v66, 0xba000000, v153
	v_fmac_f32_e32 v67, 0xba000000, v153
	v_fmac_f32_e32 v68, 0xba000000, v153
	v_fmac_f32_e32 v69, 0xba000000, v153
	v_fmac_f32_e32 v70, 0xba000000, v153
	v_fmac_f32_e32 v71, 0xba000000, v153
	v_fmac_f32_e32 v72, 0xba000000, v153
	v_fmac_f32_e32 v73, 0xba000000, v153
	v_fmac_f32_e32 v74, 0xba000000, v153
	v_fmac_f32_e32 v75, 0xba000000, v153
	v_fmac_f32_e32 v76, 0xba000000, v153
	v_fmac_f32_e32 v77, 0xba000000, v153
	v_fmac_f32_e32 v78, 0xba000000, v153
	v_fmac_f32_e32 v79, 0xba000000, v153
	v_fmac_f32_e32 v80, 0xba000000, v153
	v_fmac_f32_e32 v81, 0xba000000, v153
	v_fmac_f32_e32 v82, 0xba000000, v153
	v_fmac_f32_e32 v83, 0xba000000, v153
	v_fmac_f32_e32 v84, 0xba000000, v153
	v_fmac_f32_e32 v85, 0xba000000, v153
	v_fmac_f32_e32 v86, 0xba000000, v153
	v_fmac_f32_e32 v87, 0xba000000, v153
	v_fmac_f32_e32 v88, 0xba000000, v153
	v_fmac_f32_e32 v89, 0xba000000, v153
	v_fmac_f32_e32 v90, 0xba000000, v153
	v_fmac_f32_e32 v91, 0xba000000, v153
	v_fmac_f32_e32 v92, 0xba000000, v153
	v_fmac_f32_e32 v93, 0xba000000, v153
	v_fmac_f32_e32 v94, 0xba000000, v153
	v_fmac_f32_e32 v95, 0xba000000, v153
	v_fmac_f32_e32 v96, 0xba000000, v153
	v_fmac_f32_e32 v97, 0xba000000, v153
	v_mul_f32_e32 v151, v67, v67
	v_fma_f32 v151, v66, v66, v151
	v_mul_f32_e32 v155, v69, v69
	v_fma_f32 v155, v68, v68, v155
	v_add_f32_e32 v151, v151, v155
	v_add_f32_e32 v157, 0, v151
	v_mul_f32_e32 v151, v71, v71
	v_fma_f32 v151, v70, v70, v151
	v_mul_f32_e32 v155, v73, v73
	v_fma_f32 v155, v72, v72, v155
	v_add_f32_e32 v151, v151, v155
	v_add_f32_e32 v157, v157, v151
	v_mul_f32_e32 v151, v75, v75
	v_fma_f32 v151, v74, v74, v151
	v_mul_f32_e32 v155, v77, v77
	v_fma_f32 v155, v76, v76, v155
	v_add_f32_e32 v151, v151, v155
	v_add_f32_e32 v157, v157, v151
	v_mul_f32_e32 v151, v79, v79
	v_fma_f32 v151, v78, v78, v151
	v_mul_f32_e32 v155, v81, v81
	v_fma_f32 v155, v80, v80, v155
	v_add_f32_e32 v151, v151, v155
	v_add_f32_e32 v157, v157, v151
	v_mul_f32_e32 v151, v83, v83
	v_fma_f32 v151, v82, v82, v151
	v_mul_f32_e32 v155, v85, v85
	v_fma_f32 v155, v84, v84, v155
	v_add_f32_e32 v151, v151, v155
	v_add_f32_e32 v157, v157, v151
	v_mul_f32_e32 v151, v87, v87
	v_fma_f32 v151, v86, v86, v151
	v_mul_f32_e32 v155, v89, v89
	v_fma_f32 v155, v88, v88, v155
	v_add_f32_e32 v151, v151, v155
	v_add_f32_e32 v157, v157, v151
	v_mul_f32_e32 v151, v91, v91
	v_fma_f32 v151, v90, v90, v151
	v_mul_f32_e32 v155, v93, v93
	v_fma_f32 v155, v92, v92, v155
	v_add_f32_e32 v151, v151, v155
	v_add_f32_e32 v157, v157, v151
	v_mul_f32_e32 v151, v95, v95
	v_fma_f32 v151, v94, v94, v151
	v_mul_f32_e32 v155, v97, v97
	v_fma_f32 v155, v96, v96, v155
	v_add_f32_e32 v151, v151, v155
	v_add_f32_e32 v157, v157, v151
	ds_bpermute_b32 v151, v99, v157
	s_waitcnt lgkmcnt(0)
	v_add_f32_e32 v157, v157, v151
	ds_bpermute_b32 v151, v101, v157
	s_waitcnt lgkmcnt(0)
	v_add_f32_e32 v157, v157, v151
	ds_bpermute_b32 v151, v103, v157
	s_waitcnt lgkmcnt(0)
	v_add_f32_e32 v157, v157, v151
	ds_bpermute_b32 v151, v105, v157
	s_waitcnt lgkmcnt(0)
	v_add_f32_e32 v157, v157, v151
	ds_bpermute_b32 v151, v107, v157
	s_waitcnt lgkmcnt(0)
	v_add_f32_e32 v157, v157, v151
	ds_bpermute_b32 v151, v119, v157
	s_waitcnt lgkmcnt(0)
	v_add_f32_e32 v157, v157, v151
	v_mov_b32_e32 v254, 0x3727c5ac
	v_fmamk_f32 v157, v157, 0x3a000000, v254
	v_mul_f32_e32 v151, 0x4f800000, v157
	s_mov_b32 s9, 0xf800000
	v_cmp_gt_f32_e32 vcc, s9, v157
	s_nop 1
	v_cndmask_b32_e32 v157, v157, v151, vcc
	v_sqrt_f32_e32 v151, v157
	s_nop 0
	v_add_u32_e32 v203, -1, v151
	v_fma_f32 v204, -v203, v151, v157
	v_cmp_ge_f32_e64 s[88:89], 0, v204
	v_add_u32_e32 v204, 1, v151
	s_nop 0
	v_cndmask_b32_e64 v203, v151, v203, s[88:89]
	v_fma_f32 v151, -v204, v151, v157
	v_cmp_lt_f32_e64 s[88:89], 0, v151
	s_nop 1
	v_cndmask_b32_e64 v151, v203, v204, s[88:89]
	v_mul_f32_e32 v203, 0x37800000, v151
	v_cndmask_b32_e32 v151, v151, v203, vcc
	v_mov_b32_e32 v203, 0x260
	v_cmp_class_f32_e32 vcc, v157, v203
	s_nop 1
	v_cndmask_b32_e32 v157, v151, v157, vcc
	v_div_scale_f32 v151, s[88:89], v157, v157, 1.0
	v_rcp_f32_e32 v203, v151
	s_nop 0
	v_fma_f32 v204, -v151, v203, 1.0
	v_fmac_f32_e32 v203, v204, v203
	v_div_scale_f32 v204, vcc, 1.0, v157, 1.0
	v_mul_f32_e32 v205, v204, v203
	v_fma_f32 v254, -v151, v205, v204
	v_fmac_f32_e32 v205, v254, v203
	v_fma_f32 v151, -v151, v205, v204
	v_div_fmas_f32 v151, v151, v203, v205
	v_div_fixup_f32 v155, v151, v157, 1.0
	v_mul_f32_e32 v66, v66, v155
	v_mul_f32_e32 v67, v67, v155
	v_mul_f32_e32 v68, v68, v155
	v_mul_f32_e32 v69, v69, v155
	v_pk_fma_f32 v[66:67], v[2:3], v[66:67], v[10:11]
	v_pk_fma_f32 v[68:69], v[4:5], v[68:69], v[12:13]
	global_store_dwordx4 v129, v[66:69], s[6:7]
	s_waitcnt vmcnt(15)
	v_pk_add_f32 v[158:159], v[158:159], 1.0 op_sel_hi:[1,0]
	v_pk_add_f32 v[160:161], v[160:161], 1.0 op_sel_hi:[1,0]
	v_pk_fma_f32 v[158:159], v[158:159], v[66:67], v[220:221]
	v_pk_fma_f32 v[160:161], v[160:161], v[68:69], v[222:223]
	v_cvt_pk_bf16_f32 v158, v158, v159
	v_cvt_pk_bf16_f32 v159, v160, v161
	global_store_dwordx2 v117, v[158:159], s[10:11]
	v_mul_f32_e32 v70, v70, v155
	v_mul_f32_e32 v71, v71, v155
	v_mul_f32_e32 v72, v72, v155
	v_mul_f32_e32 v73, v73, v155
	v_pk_fma_f32 v[70:71], v[6:7], v[70:71], v[14:15]
	v_pk_fma_f32 v[72:73], v[8:9], v[72:73], v[16:17]
	global_store_dwordx4 v129, v[70:73], s[6:7] offset:1024
	s_waitcnt vmcnt(15)
	v_pk_add_f32 v[162:163], v[162:163], 1.0 op_sel_hi:[1,0]
	v_pk_add_f32 v[164:165], v[164:165], 1.0 op_sel_hi:[1,0]
	v_pk_fma_f32 v[162:163], v[162:163], v[70:71], v[224:225]
	v_pk_fma_f32 v[164:165], v[164:165], v[72:73], v[226:227]
	v_cvt_pk_bf16_f32 v162, v162, v163
	v_cvt_pk_bf16_f32 v163, v164, v165
	global_store_dwordx2 v117, v[162:163], s[10:11] offset:512
	v_mul_f32_e32 v74, v74, v155
	v_mul_f32_e32 v75, v75, v155
	v_mul_f32_e32 v76, v76, v155
	v_mul_f32_e32 v77, v77, v155
	v_pk_fma_f32 v[74:75], v[18:19], v[74:75], v[26:27]
	v_pk_fma_f32 v[76:77], v[20:21], v[76:77], v[28:29]
	global_store_dwordx4 v129, v[74:77], s[6:7] offset:2048
	s_waitcnt vmcnt(15)
	v_pk_add_f32 v[166:167], v[166:167], 1.0 op_sel_hi:[1,0]
	v_pk_add_f32 v[168:169], v[168:169], 1.0 op_sel_hi:[1,0]
	v_pk_fma_f32 v[166:167], v[166:167], v[74:75], v[228:229]
	v_pk_fma_f32 v[168:169], v[168:169], v[76:77], v[230:231]
	v_cvt_pk_bf16_f32 v166, v166, v167
	v_cvt_pk_bf16_f32 v167, v168, v169
	global_store_dwordx2 v117, v[166:167], s[10:11] offset:1024
	v_mul_f32_e32 v78, v78, v155
	v_mul_f32_e32 v79, v79, v155
	v_mul_f32_e32 v80, v80, v155
	v_mul_f32_e32 v81, v81, v155
	v_pk_fma_f32 v[78:79], v[22:23], v[78:79], v[30:31]
	v_pk_fma_f32 v[80:81], v[24:25], v[80:81], v[32:33]
	global_store_dwordx4 v129, v[78:81], s[6:7] offset:3072
	s_waitcnt vmcnt(15)
	v_pk_add_f32 v[176:177], v[176:177], 1.0 op_sel_hi:[1,0]
	v_pk_add_f32 v[178:179], v[178:179], 1.0 op_sel_hi:[1,0]
	v_pk_fma_f32 v[176:177], v[176:177], v[78:79], v[232:233]
	v_pk_fma_f32 v[178:179], v[178:179], v[80:81], v[234:235]
	v_cvt_pk_bf16_f32 v176, v176, v177
	v_cvt_pk_bf16_f32 v177, v178, v179
	global_store_dwordx2 v117, v[176:177], s[10:11] offset:1536
	v_mul_f32_e32 v82, v82, v155
	v_mul_f32_e32 v83, v83, v155
	v_mul_f32_e32 v84, v84, v155
	v_mul_f32_e32 v85, v85, v155
	v_pk_fma_f32 v[82:83], v[34:35], v[82:83], v[42:43]
	v_pk_fma_f32 v[84:85], v[36:37], v[84:85], v[44:45]
	global_store_dwordx4 v131, v[82:85], s[6:7]
	s_waitcnt vmcnt(15)
	v_pk_add_f32 v[180:181], v[180:181], 1.0 op_sel_hi:[1,0]
	v_pk_add_f32 v[182:183], v[182:183], 1.0 op_sel_hi:[1,0]
	v_pk_fma_f32 v[180:181], v[180:181], v[82:83], v[236:237]
	v_pk_fma_f32 v[182:183], v[182:183], v[84:85], v[238:239]
	v_cvt_pk_bf16_f32 v180, v180, v181
	v_cvt_pk_bf16_f32 v181, v182, v183
	global_store_dwordx2 v117, v[180:181], s[10:11] offset:2048
	v_mul_f32_e32 v86, v86, v155
	v_mul_f32_e32 v87, v87, v155
	v_mul_f32_e32 v88, v88, v155
	v_mul_f32_e32 v89, v89, v155
	v_pk_fma_f32 v[86:87], v[38:39], v[86:87], v[46:47]
	v_pk_fma_f32 v[88:89], v[40:41], v[88:89], v[48:49]
	global_store_dwordx4 v131, v[86:89], s[6:7] offset:1024
	s_waitcnt vmcnt(15)
	v_pk_add_f32 v[184:185], v[184:185], 1.0 op_sel_hi:[1,0]
	v_pk_add_f32 v[186:187], v[186:187], 1.0 op_sel_hi:[1,0]
	v_pk_fma_f32 v[184:185], v[184:185], v[86:87], v[240:241]
	v_pk_fma_f32 v[186:187], v[186:187], v[88:89], v[242:243]
	v_cvt_pk_bf16_f32 v184, v184, v185
	v_cvt_pk_bf16_f32 v185, v186, v187
	global_store_dwordx2 v117, v[184:185], s[10:11] offset:2560
	v_mul_f32_e32 v90, v90, v155
	v_mul_f32_e32 v91, v91, v155
	v_mul_f32_e32 v92, v92, v155
	v_mul_f32_e32 v93, v93, v155
	v_pk_fma_f32 v[90:91], v[50:51], v[90:91], v[58:59]
	v_pk_fma_f32 v[92:93], v[52:53], v[92:93], v[60:61]
	global_store_dwordx4 v131, v[90:93], s[6:7] offset:2048
	s_waitcnt vmcnt(15)
	v_pk_add_f32 v[212:213], v[212:213], 1.0 op_sel_hi:[1,0]
	v_pk_add_f32 v[214:215], v[214:215], 1.0 op_sel_hi:[1,0]
	v_pk_fma_f32 v[212:213], v[212:213], v[90:91], v[244:245]
	v_pk_fma_f32 v[214:215], v[214:215], v[92:93], v[246:247]
	v_cvt_pk_bf16_f32 v212, v212, v213
	v_cvt_pk_bf16_f32 v213, v214, v215
	global_store_dwordx2 v117, v[212:213], s[10:11] offset:3072
	v_mul_f32_e32 v94, v94, v155
	v_mul_f32_e32 v95, v95, v155
	v_mul_f32_e32 v96, v96, v155
	v_mul_f32_e32 v97, v97, v155
	v_pk_fma_f32 v[94:95], v[54:55], v[94:95], v[62:63]
	v_pk_fma_f32 v[96:97], v[56:57], v[96:97], v[64:65]
	global_store_dwordx4 v131, v[94:97], s[6:7] offset:3072
	s_waitcnt vmcnt(15)
	v_pk_add_f32 v[216:217], v[216:217], 1.0 op_sel_hi:[1,0]
	v_pk_add_f32 v[218:219], v[218:219], 1.0 op_sel_hi:[1,0]
	v_pk_fma_f32 v[216:217], v[216:217], v[94:95], v[248:249]
	v_pk_fma_f32 v[218:219], v[218:219], v[96:97], v[250:251]
	v_cvt_pk_bf16_f32 v216, v216, v217
	v_cvt_pk_bf16_f32 v217, v218, v219
	global_store_dwordx2 v117, v[216:217], s[10:11] offset:3584
	s_add_i32 s0, s68, 0x1000
	s_lshl_b32 s1, s0, 13
	s_add_u32 s6, s40, s1
	s_addc_u32 s7, s41, 0
	s_lshl_b32 s1, s0, 12
	s_add_u32 s10, s44, s1
	s_addc_u32 s11, s45, 0
	s_lshr_b32 s1, s0, 11
	s_lshl_b32 s1, s1, 16
	s_add_u32 s16, s14, s1
	s_addc_u32 s17, s15, 0
	global_load_dwordx4 v[66:69], v129, s[6:7]
	global_load_dwordx4 v[70:73], v129, s[6:7] offset:1024
	global_load_dwordx4 v[74:77], v129, s[6:7] offset:2048
	global_load_dwordx4 v[78:81], v129, s[6:7] offset:3072
	global_load_dwordx4 v[82:85], v131, s[6:7]
	global_load_dwordx4 v[86:89], v131, s[6:7] offset:1024
	global_load_dwordx4 v[90:93], v131, s[6:7] offset:2048
	global_load_dwordx4 v[94:97], v131, s[6:7] offset:3072
	v_lshlrev_b32_e32 v151, 2, v116
	global_load_dwordx4 v[158:161], v151, s[16:17]
	v_lshlrev_b32_e32 v151, 2, v118
	global_load_dwordx4 v[220:223], v151, s[16:17]
	v_lshlrev_b32_e32 v151, 2, v120
	global_load_dwordx4 v[162:165], v151, s[16:17]
	v_lshlrev_b32_e32 v151, 2, v122
	global_load_dwordx4 v[224:227], v151, s[16:17]
	v_lshlrev_b32_e32 v151, 2, v124
	global_load_dwordx4 v[166:169], v151, s[16:17]
	v_lshlrev_b32_e32 v151, 2, v126
	global_load_dwordx4 v[228:231], v151, s[16:17]
	v_lshlrev_b32_e32 v151, 2, v128
	global_load_dwordx4 v[176:179], v151, s[16:17]
	v_lshlrev_b32_e32 v151, 2, v130
	global_load_dwordx4 v[232:235], v151, s[16:17]
	v_lshlrev_b32_e32 v151, 2, v132
	global_load_dwordx4 v[180:183], v151, s[16:17]
	v_lshlrev_b32_e32 v151, 2, v134
	global_load_dwordx4 v[236:239], v151, s[16:17]
	v_lshlrev_b32_e32 v151, 2, v136
	global_load_dwordx4 v[184:187], v151, s[16:17]
	v_lshlrev_b32_e32 v151, 2, v138
	global_load_dwordx4 v[240:243], v151, s[16:17]
	v_lshlrev_b32_e32 v151, 2, v140
	global_load_dwordx4 v[212:215], v151, s[16:17]
	v_lshlrev_b32_e32 v151, 2, v142
	global_load_dwordx4 v[244:247], v151, s[16:17]
	v_lshlrev_b32_e32 v151, 2, v144
	global_load_dwordx4 v[216:219], v151, s[16:17]
	v_lshlrev_b32_e32 v151, 2, v146
	global_load_dwordx4 v[248:251], v151, s[16:17]
	s_waitcnt vmcnt(23)
	v_add_f32_e32 v151, v66, v67
	v_add_f32_e32 v155, v68, v69
	v_add_f32_e32 v151, v151, v155
	v_add_f32_e32 v153, 0, v151
	s_waitcnt vmcnt(22)
	v_add_f32_e32 v151, v70, v71
	v_add_f32_e32 v155, v72, v73
	v_add_f32_e32 v151, v151, v155
	v_add_f32_e32 v153, v153, v151
	s_waitcnt vmcnt(21)
	v_add_f32_e32 v151, v74, v75
	v_add_f32_e32 v155, v76, v77
	v_add_f32_e32 v151, v151, v155
	v_add_f32_e32 v153, v153, v151
	s_waitcnt vmcnt(20)
	v_add_f32_e32 v151, v78, v79
	v_add_f32_e32 v155, v80, v81
	v_add_f32_e32 v151, v151, v155
	v_add_f32_e32 v153, v153, v151
	s_waitcnt vmcnt(19)
	v_add_f32_e32 v151, v82, v83
	v_add_f32_e32 v155, v84, v85
	v_add_f32_e32 v151, v151, v155
	v_add_f32_e32 v153, v153, v151
	s_waitcnt vmcnt(18)
	v_add_f32_e32 v151, v86, v87
	v_add_f32_e32 v155, v88, v89
	v_add_f32_e32 v151, v151, v155
	v_add_f32_e32 v153, v153, v151
	s_waitcnt vmcnt(17)
	v_add_f32_e32 v151, v90, v91
	v_add_f32_e32 v155, v92, v93
	v_add_f32_e32 v151, v151, v155
	v_add_f32_e32 v153, v153, v151
	s_waitcnt vmcnt(16)
	v_add_f32_e32 v151, v94, v95
	v_add_f32_e32 v155, v96, v97
	v_add_f32_e32 v151, v151, v155
	v_add_f32_e32 v153, v153, v151
	ds_bpermute_b32 v151, v99, v153
	s_waitcnt lgkmcnt(0)
	v_add_f32_e32 v153, v153, v151
	ds_bpermute_b32 v151, v101, v153
	s_waitcnt lgkmcnt(0)
	v_add_f32_e32 v153, v153, v151
	ds_bpermute_b32 v151, v103, v153
	s_waitcnt lgkmcnt(0)
	v_add_f32_e32 v153, v153, v151
	ds_bpermute_b32 v151, v105, v153
	s_waitcnt lgkmcnt(0)
	v_add_f32_e32 v153, v153, v151
	ds_bpermute_b32 v151, v107, v153
	s_waitcnt lgkmcnt(0)
	v_add_f32_e32 v153, v153, v151
	ds_bpermute_b32 v151, v119, v153
	s_waitcnt lgkmcnt(0)
	v_add_f32_e32 v153, v153, v151
	v_fmac_f32_e32 v66, 0xba000000, v153
	v_fmac_f32_e32 v67, 0xba000000, v153
	v_fmac_f32_e32 v68, 0xba000000, v153
	v_fmac_f32_e32 v69, 0xba000000, v153
	v_fmac_f32_e32 v70, 0xba000000, v153
	v_fmac_f32_e32 v71, 0xba000000, v153
	v_fmac_f32_e32 v72, 0xba000000, v153
	v_fmac_f32_e32 v73, 0xba000000, v153
	v_fmac_f32_e32 v74, 0xba000000, v153
	v_fmac_f32_e32 v75, 0xba000000, v153
	v_fmac_f32_e32 v76, 0xba000000, v153
	v_fmac_f32_e32 v77, 0xba000000, v153
	v_fmac_f32_e32 v78, 0xba000000, v153
	v_fmac_f32_e32 v79, 0xba000000, v153
	v_fmac_f32_e32 v80, 0xba000000, v153
	v_fmac_f32_e32 v81, 0xba000000, v153
	v_fmac_f32_e32 v82, 0xba000000, v153
	v_fmac_f32_e32 v83, 0xba000000, v153
	v_fmac_f32_e32 v84, 0xba000000, v153
	v_fmac_f32_e32 v85, 0xba000000, v153
	v_fmac_f32_e32 v86, 0xba000000, v153
	v_fmac_f32_e32 v87, 0xba000000, v153
	v_fmac_f32_e32 v88, 0xba000000, v153
	v_fmac_f32_e32 v89, 0xba000000, v153
	v_fmac_f32_e32 v90, 0xba000000, v153
	v_fmac_f32_e32 v91, 0xba000000, v153
	v_fmac_f32_e32 v92, 0xba000000, v153
	v_fmac_f32_e32 v93, 0xba000000, v153
	v_fmac_f32_e32 v94, 0xba000000, v153
	v_fmac_f32_e32 v95, 0xba000000, v153
	v_fmac_f32_e32 v96, 0xba000000, v153
	v_fmac_f32_e32 v97, 0xba000000, v153
	v_mul_f32_e32 v151, v67, v67
	v_fma_f32 v151, v66, v66, v151
	v_mul_f32_e32 v155, v69, v69
	v_fma_f32 v155, v68, v68, v155
	v_add_f32_e32 v151, v151, v155
	v_add_f32_e32 v157, 0, v151
	v_mul_f32_e32 v151, v71, v71
	v_fma_f32 v151, v70, v70, v151
	v_mul_f32_e32 v155, v73, v73
	v_fma_f32 v155, v72, v72, v155
	v_add_f32_e32 v151, v151, v155
	v_add_f32_e32 v157, v157, v151
	v_mul_f32_e32 v151, v75, v75
	v_fma_f32 v151, v74, v74, v151
	v_mul_f32_e32 v155, v77, v77
	v_fma_f32 v155, v76, v76, v155
	v_add_f32_e32 v151, v151, v155
	v_add_f32_e32 v157, v157, v151
	v_mul_f32_e32 v151, v79, v79
	v_fma_f32 v151, v78, v78, v151
	v_mul_f32_e32 v155, v81, v81
	v_fma_f32 v155, v80, v80, v155
	v_add_f32_e32 v151, v151, v155
	v_add_f32_e32 v157, v157, v151
	v_mul_f32_e32 v151, v83, v83
	v_fma_f32 v151, v82, v82, v151
	v_mul_f32_e32 v155, v85, v85
	v_fma_f32 v155, v84, v84, v155
	v_add_f32_e32 v151, v151, v155
	v_add_f32_e32 v157, v157, v151
	v_mul_f32_e32 v151, v87, v87
	v_fma_f32 v151, v86, v86, v151
	v_mul_f32_e32 v155, v89, v89
	v_fma_f32 v155, v88, v88, v155
	v_add_f32_e32 v151, v151, v155
	v_add_f32_e32 v157, v157, v151
	v_mul_f32_e32 v151, v91, v91
	v_fma_f32 v151, v90, v90, v151
	v_mul_f32_e32 v155, v93, v93
	v_fma_f32 v155, v92, v92, v155
	v_add_f32_e32 v151, v151, v155
	v_add_f32_e32 v157, v157, v151
	v_mul_f32_e32 v151, v95, v95
	v_fma_f32 v151, v94, v94, v151
	v_mul_f32_e32 v155, v97, v97
	v_fma_f32 v155, v96, v96, v155
	v_add_f32_e32 v151, v151, v155
	v_add_f32_e32 v157, v157, v151
	ds_bpermute_b32 v151, v99, v157
	s_waitcnt lgkmcnt(0)
	v_add_f32_e32 v157, v157, v151
	ds_bpermute_b32 v151, v101, v157
	s_waitcnt lgkmcnt(0)
	v_add_f32_e32 v157, v157, v151
	ds_bpermute_b32 v151, v103, v157
	s_waitcnt lgkmcnt(0)
	v_add_f32_e32 v157, v157, v151
	ds_bpermute_b32 v151, v105, v157
	s_waitcnt lgkmcnt(0)
	v_add_f32_e32 v157, v157, v151
	ds_bpermute_b32 v151, v107, v157
	s_waitcnt lgkmcnt(0)
	v_add_f32_e32 v157, v157, v151
	ds_bpermute_b32 v151, v119, v157
	s_waitcnt lgkmcnt(0)
	v_add_f32_e32 v157, v157, v151
	v_mov_b32_e32 v254, 0x3727c5ac
	v_fmamk_f32 v157, v157, 0x3a000000, v254
	v_mul_f32_e32 v151, 0x4f800000, v157
	s_mov_b32 s9, 0xf800000
	v_cmp_gt_f32_e32 vcc, s9, v157
	s_nop 1
	v_cndmask_b32_e32 v157, v157, v151, vcc
	v_sqrt_f32_e32 v151, v157
	s_nop 0
	v_add_u32_e32 v203, -1, v151
	v_fma_f32 v204, -v203, v151, v157
	v_cmp_ge_f32_e64 s[88:89], 0, v204
	v_add_u32_e32 v204, 1, v151
	s_nop 0
	v_cndmask_b32_e64 v203, v151, v203, s[88:89]
	v_fma_f32 v151, -v204, v151, v157
	v_cmp_lt_f32_e64 s[88:89], 0, v151
	s_nop 1
	v_cndmask_b32_e64 v151, v203, v204, s[88:89]
	v_mul_f32_e32 v203, 0x37800000, v151
	v_cndmask_b32_e32 v151, v151, v203, vcc
	v_mov_b32_e32 v203, 0x260
	v_cmp_class_f32_e32 vcc, v157, v203
	s_nop 1
	v_cndmask_b32_e32 v157, v151, v157, vcc
	v_div_scale_f32 v151, s[88:89], v157, v157, 1.0
	v_rcp_f32_e32 v203, v151
	s_nop 0
	v_fma_f32 v204, -v151, v203, 1.0
	v_fmac_f32_e32 v203, v204, v203
	v_div_scale_f32 v204, vcc, 1.0, v157, 1.0
	v_mul_f32_e32 v205, v204, v203
	v_fma_f32 v254, -v151, v205, v204
	v_fmac_f32_e32 v205, v254, v203
	v_fma_f32 v151, -v151, v205, v204
	v_div_fmas_f32 v151, v151, v203, v205
	v_div_fixup_f32 v155, v151, v157, 1.0
	v_mul_f32_e32 v66, v66, v155
	v_mul_f32_e32 v67, v67, v155
	v_mul_f32_e32 v68, v68, v155
	v_mul_f32_e32 v69, v69, v155
	v_pk_fma_f32 v[66:67], v[2:3], v[66:67], v[10:11]
	v_pk_fma_f32 v[68:69], v[4:5], v[68:69], v[12:13]
	global_store_dwordx4 v129, v[66:69], s[6:7]
	s_waitcnt vmcnt(15)
	v_pk_add_f32 v[158:159], v[158:159], 1.0 op_sel_hi:[1,0]
	v_pk_add_f32 v[160:161], v[160:161], 1.0 op_sel_hi:[1,0]
	v_pk_fma_f32 v[158:159], v[158:159], v[66:67], v[220:221]
	v_pk_fma_f32 v[160:161], v[160:161], v[68:69], v[222:223]
	v_cvt_pk_bf16_f32 v158, v158, v159
	v_cvt_pk_bf16_f32 v159, v160, v161
	global_store_dwordx2 v117, v[158:159], s[10:11]
	v_mul_f32_e32 v70, v70, v155
	v_mul_f32_e32 v71, v71, v155
	v_mul_f32_e32 v72, v72, v155
	v_mul_f32_e32 v73, v73, v155
	v_pk_fma_f32 v[70:71], v[6:7], v[70:71], v[14:15]
	v_pk_fma_f32 v[72:73], v[8:9], v[72:73], v[16:17]
	global_store_dwordx4 v129, v[70:73], s[6:7] offset:1024
	s_waitcnt vmcnt(15)
	v_pk_add_f32 v[162:163], v[162:163], 1.0 op_sel_hi:[1,0]
	v_pk_add_f32 v[164:165], v[164:165], 1.0 op_sel_hi:[1,0]
	v_pk_fma_f32 v[162:163], v[162:163], v[70:71], v[224:225]
	v_pk_fma_f32 v[164:165], v[164:165], v[72:73], v[226:227]
	v_cvt_pk_bf16_f32 v162, v162, v163
	v_cvt_pk_bf16_f32 v163, v164, v165
	global_store_dwordx2 v117, v[162:163], s[10:11] offset:512
	v_mul_f32_e32 v74, v74, v155
	v_mul_f32_e32 v75, v75, v155
	v_mul_f32_e32 v76, v76, v155
	v_mul_f32_e32 v77, v77, v155
	v_pk_fma_f32 v[74:75], v[18:19], v[74:75], v[26:27]
	v_pk_fma_f32 v[76:77], v[20:21], v[76:77], v[28:29]
	global_store_dwordx4 v129, v[74:77], s[6:7] offset:2048
	s_waitcnt vmcnt(15)
	v_pk_add_f32 v[166:167], v[166:167], 1.0 op_sel_hi:[1,0]
	v_pk_add_f32 v[168:169], v[168:169], 1.0 op_sel_hi:[1,0]
	v_pk_fma_f32 v[166:167], v[166:167], v[74:75], v[228:229]
	v_pk_fma_f32 v[168:169], v[168:169], v[76:77], v[230:231]
	v_cvt_pk_bf16_f32 v166, v166, v167
	v_cvt_pk_bf16_f32 v167, v168, v169
	global_store_dwordx2 v117, v[166:167], s[10:11] offset:1024
	v_mul_f32_e32 v78, v78, v155
	v_mul_f32_e32 v79, v79, v155
	v_mul_f32_e32 v80, v80, v155
	v_mul_f32_e32 v81, v81, v155
	v_pk_fma_f32 v[78:79], v[22:23], v[78:79], v[30:31]
	v_pk_fma_f32 v[80:81], v[24:25], v[80:81], v[32:33]
	global_store_dwordx4 v129, v[78:81], s[6:7] offset:3072
	s_waitcnt vmcnt(15)
	v_pk_add_f32 v[176:177], v[176:177], 1.0 op_sel_hi:[1,0]
	v_pk_add_f32 v[178:179], v[178:179], 1.0 op_sel_hi:[1,0]
	v_pk_fma_f32 v[176:177], v[176:177], v[78:79], v[232:233]
	v_pk_fma_f32 v[178:179], v[178:179], v[80:81], v[234:235]
	v_cvt_pk_bf16_f32 v176, v176, v177
	v_cvt_pk_bf16_f32 v177, v178, v179
	global_store_dwordx2 v117, v[176:177], s[10:11] offset:1536
	v_mul_f32_e32 v82, v82, v155
	v_mul_f32_e32 v83, v83, v155
	v_mul_f32_e32 v84, v84, v155
	v_mul_f32_e32 v85, v85, v155
	v_pk_fma_f32 v[82:83], v[34:35], v[82:83], v[42:43]
	v_pk_fma_f32 v[84:85], v[36:37], v[84:85], v[44:45]
	global_store_dwordx4 v131, v[82:85], s[6:7]
	s_waitcnt vmcnt(15)
	v_pk_add_f32 v[180:181], v[180:181], 1.0 op_sel_hi:[1,0]
	v_pk_add_f32 v[182:183], v[182:183], 1.0 op_sel_hi:[1,0]
	v_pk_fma_f32 v[180:181], v[180:181], v[82:83], v[236:237]
	v_pk_fma_f32 v[182:183], v[182:183], v[84:85], v[238:239]
	v_cvt_pk_bf16_f32 v180, v180, v181
	v_cvt_pk_bf16_f32 v181, v182, v183
	global_store_dwordx2 v117, v[180:181], s[10:11] offset:2048
	v_mul_f32_e32 v86, v86, v155
	v_mul_f32_e32 v87, v87, v155
	v_mul_f32_e32 v88, v88, v155
	v_mul_f32_e32 v89, v89, v155
	v_pk_fma_f32 v[86:87], v[38:39], v[86:87], v[46:47]
	v_pk_fma_f32 v[88:89], v[40:41], v[88:89], v[48:49]
	global_store_dwordx4 v131, v[86:89], s[6:7] offset:1024
	s_waitcnt vmcnt(15)
	v_pk_add_f32 v[184:185], v[184:185], 1.0 op_sel_hi:[1,0]
	v_pk_add_f32 v[186:187], v[186:187], 1.0 op_sel_hi:[1,0]
	v_pk_fma_f32 v[184:185], v[184:185], v[86:87], v[240:241]
	v_pk_fma_f32 v[186:187], v[186:187], v[88:89], v[242:243]
	v_cvt_pk_bf16_f32 v184, v184, v185
	v_cvt_pk_bf16_f32 v185, v186, v187
	global_store_dwordx2 v117, v[184:185], s[10:11] offset:2560
	v_mul_f32_e32 v90, v90, v155
	v_mul_f32_e32 v91, v91, v155
	v_mul_f32_e32 v92, v92, v155
	v_mul_f32_e32 v93, v93, v155
	v_pk_fma_f32 v[90:91], v[50:51], v[90:91], v[58:59]
	v_pk_fma_f32 v[92:93], v[52:53], v[92:93], v[60:61]
	global_store_dwordx4 v131, v[90:93], s[6:7] offset:2048
	s_waitcnt vmcnt(15)
	v_pk_add_f32 v[212:213], v[212:213], 1.0 op_sel_hi:[1,0]
	v_pk_add_f32 v[214:215], v[214:215], 1.0 op_sel_hi:[1,0]
	v_pk_fma_f32 v[212:213], v[212:213], v[90:91], v[244:245]
	v_pk_fma_f32 v[214:215], v[214:215], v[92:93], v[246:247]
	v_cvt_pk_bf16_f32 v212, v212, v213
	v_cvt_pk_bf16_f32 v213, v214, v215
	global_store_dwordx2 v117, v[212:213], s[10:11] offset:3072
	v_mul_f32_e32 v94, v94, v155
	v_mul_f32_e32 v95, v95, v155
	v_mul_f32_e32 v96, v96, v155
	v_mul_f32_e32 v97, v97, v155
	v_pk_fma_f32 v[94:95], v[54:55], v[94:95], v[62:63]
	v_pk_fma_f32 v[96:97], v[56:57], v[96:97], v[64:65]
	global_store_dwordx4 v131, v[94:97], s[6:7] offset:3072
	s_waitcnt vmcnt(15)
	v_pk_add_f32 v[216:217], v[216:217], 1.0 op_sel_hi:[1,0]
	v_pk_add_f32 v[218:219], v[218:219], 1.0 op_sel_hi:[1,0]
	v_pk_fma_f32 v[216:217], v[216:217], v[94:95], v[248:249]
	v_pk_fma_f32 v[218:219], v[218:219], v[96:97], v[250:251]
	v_cvt_pk_bf16_f32 v216, v216, v217
	v_cvt_pk_bf16_f32 v217, v218, v219
	global_store_dwordx2 v117, v[216:217], s[10:11] offset:3584
	s_add_i32 s0, s68, 0x1800
	s_lshl_b32 s1, s0, 13
	s_add_u32 s6, s40, s1
	s_addc_u32 s7, s41, 0
	s_lshl_b32 s1, s0, 12
	s_add_u32 s10, s44, s1
	s_addc_u32 s11, s45, 0
	s_lshr_b32 s1, s0, 11
	s_lshl_b32 s1, s1, 16
	s_add_u32 s16, s14, s1
	s_addc_u32 s17, s15, 0
	global_load_dwordx4 v[66:69], v129, s[6:7]
	global_load_dwordx4 v[70:73], v129, s[6:7] offset:1024
	global_load_dwordx4 v[74:77], v129, s[6:7] offset:2048
	global_load_dwordx4 v[78:81], v129, s[6:7] offset:3072
	global_load_dwordx4 v[82:85], v131, s[6:7]
	global_load_dwordx4 v[86:89], v131, s[6:7] offset:1024
	global_load_dwordx4 v[90:93], v131, s[6:7] offset:2048
	global_load_dwordx4 v[94:97], v131, s[6:7] offset:3072
	v_lshlrev_b32_e32 v151, 2, v116
	global_load_dwordx4 v[158:161], v151, s[16:17]
	v_lshlrev_b32_e32 v151, 2, v118
	global_load_dwordx4 v[220:223], v151, s[16:17]
	v_lshlrev_b32_e32 v151, 2, v120
	global_load_dwordx4 v[162:165], v151, s[16:17]
	v_lshlrev_b32_e32 v151, 2, v122
	global_load_dwordx4 v[224:227], v151, s[16:17]
	v_lshlrev_b32_e32 v151, 2, v124
	global_load_dwordx4 v[166:169], v151, s[16:17]
	v_lshlrev_b32_e32 v151, 2, v126
	global_load_dwordx4 v[228:231], v151, s[16:17]
	v_lshlrev_b32_e32 v151, 2, v128
	global_load_dwordx4 v[176:179], v151, s[16:17]
	v_lshlrev_b32_e32 v151, 2, v130
	global_load_dwordx4 v[232:235], v151, s[16:17]
	v_lshlrev_b32_e32 v151, 2, v132
	global_load_dwordx4 v[180:183], v151, s[16:17]
	v_lshlrev_b32_e32 v151, 2, v134
	global_load_dwordx4 v[236:239], v151, s[16:17]
	v_lshlrev_b32_e32 v151, 2, v136
	global_load_dwordx4 v[184:187], v151, s[16:17]
	v_lshlrev_b32_e32 v151, 2, v138
	global_load_dwordx4 v[240:243], v151, s[16:17]
	v_lshlrev_b32_e32 v151, 2, v140
	global_load_dwordx4 v[212:215], v151, s[16:17]
	v_lshlrev_b32_e32 v151, 2, v142
	global_load_dwordx4 v[244:247], v151, s[16:17]
	v_lshlrev_b32_e32 v151, 2, v144
	global_load_dwordx4 v[216:219], v151, s[16:17]
	v_lshlrev_b32_e32 v151, 2, v146
	global_load_dwordx4 v[248:251], v151, s[16:17]
	s_waitcnt vmcnt(23)
	v_add_f32_e32 v151, v66, v67
	v_add_f32_e32 v155, v68, v69
	v_add_f32_e32 v151, v151, v155
	v_add_f32_e32 v153, 0, v151
	s_waitcnt vmcnt(22)
	v_add_f32_e32 v151, v70, v71
	v_add_f32_e32 v155, v72, v73
	v_add_f32_e32 v151, v151, v155
	v_add_f32_e32 v153, v153, v151
	s_waitcnt vmcnt(21)
	v_add_f32_e32 v151, v74, v75
	v_add_f32_e32 v155, v76, v77
	v_add_f32_e32 v151, v151, v155
	v_add_f32_e32 v153, v153, v151
	s_waitcnt vmcnt(20)
	v_add_f32_e32 v151, v78, v79
	v_add_f32_e32 v155, v80, v81
	v_add_f32_e32 v151, v151, v155
	v_add_f32_e32 v153, v153, v151
	s_waitcnt vmcnt(19)
	v_add_f32_e32 v151, v82, v83
	v_add_f32_e32 v155, v84, v85
	v_add_f32_e32 v151, v151, v155
	v_add_f32_e32 v153, v153, v151
	s_waitcnt vmcnt(18)
	v_add_f32_e32 v151, v86, v87
	v_add_f32_e32 v155, v88, v89
	v_add_f32_e32 v151, v151, v155
	v_add_f32_e32 v153, v153, v151
	s_waitcnt vmcnt(17)
	v_add_f32_e32 v151, v90, v91
	v_add_f32_e32 v155, v92, v93
	v_add_f32_e32 v151, v151, v155
	v_add_f32_e32 v153, v153, v151
	s_waitcnt vmcnt(16)
	v_add_f32_e32 v151, v94, v95
	v_add_f32_e32 v155, v96, v97
	v_add_f32_e32 v151, v151, v155
	v_add_f32_e32 v153, v153, v151
	ds_bpermute_b32 v151, v99, v153
	s_waitcnt lgkmcnt(0)
	v_add_f32_e32 v153, v153, v151
	ds_bpermute_b32 v151, v101, v153
	s_waitcnt lgkmcnt(0)
	v_add_f32_e32 v153, v153, v151
	ds_bpermute_b32 v151, v103, v153
	s_waitcnt lgkmcnt(0)
	v_add_f32_e32 v153, v153, v151
	ds_bpermute_b32 v151, v105, v153
	s_waitcnt lgkmcnt(0)
	v_add_f32_e32 v153, v153, v151
	ds_bpermute_b32 v151, v107, v153
	s_waitcnt lgkmcnt(0)
	v_add_f32_e32 v153, v153, v151
	ds_bpermute_b32 v151, v119, v153
	s_waitcnt lgkmcnt(0)
	v_add_f32_e32 v153, v153, v151
	v_fmac_f32_e32 v66, 0xba000000, v153
	v_fmac_f32_e32 v67, 0xba000000, v153
	v_fmac_f32_e32 v68, 0xba000000, v153
	v_fmac_f32_e32 v69, 0xba000000, v153
	v_fmac_f32_e32 v70, 0xba000000, v153
	v_fmac_f32_e32 v71, 0xba000000, v153
	v_fmac_f32_e32 v72, 0xba000000, v153
	v_fmac_f32_e32 v73, 0xba000000, v153
	v_fmac_f32_e32 v74, 0xba000000, v153
	v_fmac_f32_e32 v75, 0xba000000, v153
	v_fmac_f32_e32 v76, 0xba000000, v153
	v_fmac_f32_e32 v77, 0xba000000, v153
	v_fmac_f32_e32 v78, 0xba000000, v153
	v_fmac_f32_e32 v79, 0xba000000, v153
	v_fmac_f32_e32 v80, 0xba000000, v153
	v_fmac_f32_e32 v81, 0xba000000, v153
	v_fmac_f32_e32 v82, 0xba000000, v153
	v_fmac_f32_e32 v83, 0xba000000, v153
	v_fmac_f32_e32 v84, 0xba000000, v153
	v_fmac_f32_e32 v85, 0xba000000, v153
	v_fmac_f32_e32 v86, 0xba000000, v153
	v_fmac_f32_e32 v87, 0xba000000, v153
	v_fmac_f32_e32 v88, 0xba000000, v153
	v_fmac_f32_e32 v89, 0xba000000, v153
	v_fmac_f32_e32 v90, 0xba000000, v153
	v_fmac_f32_e32 v91, 0xba000000, v153
	v_fmac_f32_e32 v92, 0xba000000, v153
	v_fmac_f32_e32 v93, 0xba000000, v153
	v_fmac_f32_e32 v94, 0xba000000, v153
	v_fmac_f32_e32 v95, 0xba000000, v153
	v_fmac_f32_e32 v96, 0xba000000, v153
	v_fmac_f32_e32 v97, 0xba000000, v153
	v_mul_f32_e32 v151, v67, v67
	v_fma_f32 v151, v66, v66, v151
	v_mul_f32_e32 v155, v69, v69
	v_fma_f32 v155, v68, v68, v155
	v_add_f32_e32 v151, v151, v155
	v_add_f32_e32 v157, 0, v151
	v_mul_f32_e32 v151, v71, v71
	v_fma_f32 v151, v70, v70, v151
	v_mul_f32_e32 v155, v73, v73
	v_fma_f32 v155, v72, v72, v155
	v_add_f32_e32 v151, v151, v155
	v_add_f32_e32 v157, v157, v151
	v_mul_f32_e32 v151, v75, v75
	v_fma_f32 v151, v74, v74, v151
	v_mul_f32_e32 v155, v77, v77
	v_fma_f32 v155, v76, v76, v155
	v_add_f32_e32 v151, v151, v155
	v_add_f32_e32 v157, v157, v151
	v_mul_f32_e32 v151, v79, v79
	v_fma_f32 v151, v78, v78, v151
	v_mul_f32_e32 v155, v81, v81
	v_fma_f32 v155, v80, v80, v155
	v_add_f32_e32 v151, v151, v155
	v_add_f32_e32 v157, v157, v151
	v_mul_f32_e32 v151, v83, v83
	v_fma_f32 v151, v82, v82, v151
	v_mul_f32_e32 v155, v85, v85
	v_fma_f32 v155, v84, v84, v155
	v_add_f32_e32 v151, v151, v155
	v_add_f32_e32 v157, v157, v151
	v_mul_f32_e32 v151, v87, v87
	v_fma_f32 v151, v86, v86, v151
	v_mul_f32_e32 v155, v89, v89
	v_fma_f32 v155, v88, v88, v155
	v_add_f32_e32 v151, v151, v155
	v_add_f32_e32 v157, v157, v151
	v_mul_f32_e32 v151, v91, v91
	v_fma_f32 v151, v90, v90, v151
	v_mul_f32_e32 v155, v93, v93
	v_fma_f32 v155, v92, v92, v155
	v_add_f32_e32 v151, v151, v155
	v_add_f32_e32 v157, v157, v151
	v_mul_f32_e32 v151, v95, v95
	v_fma_f32 v151, v94, v94, v151
	v_mul_f32_e32 v155, v97, v97
	v_fma_f32 v155, v96, v96, v155
	v_add_f32_e32 v151, v151, v155
	v_add_f32_e32 v157, v157, v151
	ds_bpermute_b32 v151, v99, v157
	s_waitcnt lgkmcnt(0)
	v_add_f32_e32 v157, v157, v151
	ds_bpermute_b32 v151, v101, v157
	s_waitcnt lgkmcnt(0)
	v_add_f32_e32 v157, v157, v151
	ds_bpermute_b32 v151, v103, v157
	s_waitcnt lgkmcnt(0)
	v_add_f32_e32 v157, v157, v151
	ds_bpermute_b32 v151, v105, v157
	s_waitcnt lgkmcnt(0)
	v_add_f32_e32 v157, v157, v151
	ds_bpermute_b32 v151, v107, v157
	s_waitcnt lgkmcnt(0)
	v_add_f32_e32 v157, v157, v151
	ds_bpermute_b32 v151, v119, v157
	s_waitcnt lgkmcnt(0)
	v_add_f32_e32 v157, v157, v151
	v_mov_b32_e32 v254, 0x3727c5ac
	v_fmamk_f32 v157, v157, 0x3a000000, v254
	v_mul_f32_e32 v151, 0x4f800000, v157
	s_mov_b32 s9, 0xf800000
	v_cmp_gt_f32_e32 vcc, s9, v157
	s_nop 1
	v_cndmask_b32_e32 v157, v157, v151, vcc
	v_sqrt_f32_e32 v151, v157
	s_nop 0
	v_add_u32_e32 v203, -1, v151
	v_fma_f32 v204, -v203, v151, v157
	v_cmp_ge_f32_e64 s[88:89], 0, v204
	v_add_u32_e32 v204, 1, v151
	s_nop 0
	v_cndmask_b32_e64 v203, v151, v203, s[88:89]
	v_fma_f32 v151, -v204, v151, v157
	v_cmp_lt_f32_e64 s[88:89], 0, v151
	s_nop 1
	v_cndmask_b32_e64 v151, v203, v204, s[88:89]
	v_mul_f32_e32 v203, 0x37800000, v151
	v_cndmask_b32_e32 v151, v151, v203, vcc
	v_mov_b32_e32 v203, 0x260
	v_cmp_class_f32_e32 vcc, v157, v203
	s_nop 1
	v_cndmask_b32_e32 v157, v151, v157, vcc
	v_div_scale_f32 v151, s[88:89], v157, v157, 1.0
	v_rcp_f32_e32 v203, v151
	s_nop 0
	v_fma_f32 v204, -v151, v203, 1.0
	v_fmac_f32_e32 v203, v204, v203
	v_div_scale_f32 v204, vcc, 1.0, v157, 1.0
	v_mul_f32_e32 v205, v204, v203
	v_fma_f32 v254, -v151, v205, v204
	v_fmac_f32_e32 v205, v254, v203
	v_fma_f32 v151, -v151, v205, v204
	v_div_fmas_f32 v151, v151, v203, v205
	v_div_fixup_f32 v155, v151, v157, 1.0
	v_mul_f32_e32 v66, v66, v155
	v_mul_f32_e32 v67, v67, v155
	v_mul_f32_e32 v68, v68, v155
	v_mul_f32_e32 v69, v69, v155
	v_pk_fma_f32 v[66:67], v[2:3], v[66:67], v[10:11]
	v_pk_fma_f32 v[68:69], v[4:5], v[68:69], v[12:13]
	global_store_dwordx4 v129, v[66:69], s[6:7]
	s_waitcnt vmcnt(15)
	v_pk_add_f32 v[158:159], v[158:159], 1.0 op_sel_hi:[1,0]
	v_pk_add_f32 v[160:161], v[160:161], 1.0 op_sel_hi:[1,0]
	v_pk_fma_f32 v[158:159], v[158:159], v[66:67], v[220:221]
	v_pk_fma_f32 v[160:161], v[160:161], v[68:69], v[222:223]
	v_cvt_pk_bf16_f32 v158, v158, v159
	v_cvt_pk_bf16_f32 v159, v160, v161
	global_store_dwordx2 v117, v[158:159], s[10:11]
	v_mul_f32_e32 v70, v70, v155
	v_mul_f32_e32 v71, v71, v155
	v_mul_f32_e32 v72, v72, v155
	v_mul_f32_e32 v73, v73, v155
	v_pk_fma_f32 v[70:71], v[6:7], v[70:71], v[14:15]
	v_pk_fma_f32 v[72:73], v[8:9], v[72:73], v[16:17]
	global_store_dwordx4 v129, v[70:73], s[6:7] offset:1024
	s_waitcnt vmcnt(15)
	v_pk_add_f32 v[162:163], v[162:163], 1.0 op_sel_hi:[1,0]
	v_pk_add_f32 v[164:165], v[164:165], 1.0 op_sel_hi:[1,0]
	v_pk_fma_f32 v[162:163], v[162:163], v[70:71], v[224:225]
	v_pk_fma_f32 v[164:165], v[164:165], v[72:73], v[226:227]
	v_cvt_pk_bf16_f32 v162, v162, v163
	v_cvt_pk_bf16_f32 v163, v164, v165
	global_store_dwordx2 v117, v[162:163], s[10:11] offset:512
	v_mul_f32_e32 v74, v74, v155
	v_mul_f32_e32 v75, v75, v155
	v_mul_f32_e32 v76, v76, v155
	v_mul_f32_e32 v77, v77, v155
	v_pk_fma_f32 v[74:75], v[18:19], v[74:75], v[26:27]
	v_pk_fma_f32 v[76:77], v[20:21], v[76:77], v[28:29]
	global_store_dwordx4 v129, v[74:77], s[6:7] offset:2048
	s_waitcnt vmcnt(15)
	v_pk_add_f32 v[166:167], v[166:167], 1.0 op_sel_hi:[1,0]
	v_pk_add_f32 v[168:169], v[168:169], 1.0 op_sel_hi:[1,0]
	v_pk_fma_f32 v[166:167], v[166:167], v[74:75], v[228:229]
	v_pk_fma_f32 v[168:169], v[168:169], v[76:77], v[230:231]
	v_cvt_pk_bf16_f32 v166, v166, v167
	v_cvt_pk_bf16_f32 v167, v168, v169
	global_store_dwordx2 v117, v[166:167], s[10:11] offset:1024
	v_mul_f32_e32 v78, v78, v155
	v_mul_f32_e32 v79, v79, v155
	v_mul_f32_e32 v80, v80, v155
	v_mul_f32_e32 v81, v81, v155
	v_pk_fma_f32 v[78:79], v[22:23], v[78:79], v[30:31]
	v_pk_fma_f32 v[80:81], v[24:25], v[80:81], v[32:33]
	global_store_dwordx4 v129, v[78:81], s[6:7] offset:3072
	s_waitcnt vmcnt(15)
	v_pk_add_f32 v[176:177], v[176:177], 1.0 op_sel_hi:[1,0]
	v_pk_add_f32 v[178:179], v[178:179], 1.0 op_sel_hi:[1,0]
	v_pk_fma_f32 v[176:177], v[176:177], v[78:79], v[232:233]
	v_pk_fma_f32 v[178:179], v[178:179], v[80:81], v[234:235]
	v_cvt_pk_bf16_f32 v176, v176, v177
	v_cvt_pk_bf16_f32 v177, v178, v179
	global_store_dwordx2 v117, v[176:177], s[10:11] offset:1536
	v_mul_f32_e32 v82, v82, v155
	v_mul_f32_e32 v83, v83, v155
	v_mul_f32_e32 v84, v84, v155
	v_mul_f32_e32 v85, v85, v155
	v_pk_fma_f32 v[82:83], v[34:35], v[82:83], v[42:43]
	v_pk_fma_f32 v[84:85], v[36:37], v[84:85], v[44:45]
	global_store_dwordx4 v131, v[82:85], s[6:7]
	s_waitcnt vmcnt(15)
	v_pk_add_f32 v[180:181], v[180:181], 1.0 op_sel_hi:[1,0]
	v_pk_add_f32 v[182:183], v[182:183], 1.0 op_sel_hi:[1,0]
	v_pk_fma_f32 v[180:181], v[180:181], v[82:83], v[236:237]
	v_pk_fma_f32 v[182:183], v[182:183], v[84:85], v[238:239]
	v_cvt_pk_bf16_f32 v180, v180, v181
	v_cvt_pk_bf16_f32 v181, v182, v183
	global_store_dwordx2 v117, v[180:181], s[10:11] offset:2048
	v_mul_f32_e32 v86, v86, v155
	v_mul_f32_e32 v87, v87, v155
	v_mul_f32_e32 v88, v88, v155
	v_mul_f32_e32 v89, v89, v155
	v_pk_fma_f32 v[86:87], v[38:39], v[86:87], v[46:47]
	v_pk_fma_f32 v[88:89], v[40:41], v[88:89], v[48:49]
	global_store_dwordx4 v131, v[86:89], s[6:7] offset:1024
	s_waitcnt vmcnt(15)
	v_pk_add_f32 v[184:185], v[184:185], 1.0 op_sel_hi:[1,0]
	v_pk_add_f32 v[186:187], v[186:187], 1.0 op_sel_hi:[1,0]
	v_pk_fma_f32 v[184:185], v[184:185], v[86:87], v[240:241]
	v_pk_fma_f32 v[186:187], v[186:187], v[88:89], v[242:243]
	v_cvt_pk_bf16_f32 v184, v184, v185
	v_cvt_pk_bf16_f32 v185, v186, v187
	global_store_dwordx2 v117, v[184:185], s[10:11] offset:2560
	v_mul_f32_e32 v90, v90, v155
	v_mul_f32_e32 v91, v91, v155
	v_mul_f32_e32 v92, v92, v155
	v_mul_f32_e32 v93, v93, v155
	v_pk_fma_f32 v[90:91], v[50:51], v[90:91], v[58:59]
	v_pk_fma_f32 v[92:93], v[52:53], v[92:93], v[60:61]
	global_store_dwordx4 v131, v[90:93], s[6:7] offset:2048
	s_waitcnt vmcnt(15)
	v_pk_add_f32 v[212:213], v[212:213], 1.0 op_sel_hi:[1,0]
	v_pk_add_f32 v[214:215], v[214:215], 1.0 op_sel_hi:[1,0]
	v_pk_fma_f32 v[212:213], v[212:213], v[90:91], v[244:245]
	v_pk_fma_f32 v[214:215], v[214:215], v[92:93], v[246:247]
	v_cvt_pk_bf16_f32 v212, v212, v213
	v_cvt_pk_bf16_f32 v213, v214, v215
	global_store_dwordx2 v117, v[212:213], s[10:11] offset:3072
	v_mul_f32_e32 v94, v94, v155
	v_mul_f32_e32 v95, v95, v155
	v_mul_f32_e32 v96, v96, v155
	v_mul_f32_e32 v97, v97, v155
	v_pk_fma_f32 v[94:95], v[54:55], v[94:95], v[62:63]
	v_pk_fma_f32 v[96:97], v[56:57], v[96:97], v[64:65]
	global_store_dwordx4 v131, v[94:97], s[6:7] offset:3072
	s_waitcnt vmcnt(15)
	v_pk_add_f32 v[216:217], v[216:217], 1.0 op_sel_hi:[1,0]
	v_pk_add_f32 v[218:219], v[218:219], 1.0 op_sel_hi:[1,0]
	v_pk_fma_f32 v[216:217], v[216:217], v[94:95], v[248:249]
	v_pk_fma_f32 v[218:219], v[218:219], v[96:97], v[250:251]
	v_cvt_pk_bf16_f32 v216, v216, v217
	v_cvt_pk_bf16_f32 v217, v218, v219
	global_store_dwordx2 v117, v[216:217], s[10:11] offset:3584
	s_cmp_gt_u32 s2, 127
	s_cbranch_scc1 .Lp6_nosample
	s_waitcnt vmcnt(0)
	v_readlane_b32 s0, v255, 5
	s_lshl_b32 s9, s0, 10
	v_add_u32_e32 v73, s9, v129
	s_lshl_b32 s9, s0, 9
	v_add_u32_e32 v74, s9, v117
	s_lshl_b32 s9, s2, 13
	s_add_u32 s32, s42, s9
	s_addc_u32 s33, s43, 0
	s_add_u32 s50, s32, 0x100000
	s_addc_u32 s51, s33, 0
	s_add_u32 s52, s50, 0x100000
	s_addc_u32 s53, s51, 0
	s_add_u32 s54, s52, 0x100000
	s_addc_u32 s55, s53, 0
	s_add_u32 s56, s54, 0x100000
	s_addc_u32 s57, s55, 0
	s_add_u32 s60, s56, 0x100000
	s_addc_u32 s61, s57, 0
	s_add_u32 s62, s60, 0x100000
	s_addc_u32 s63, s61, 0
	s_add_u32 s74, s62, 0x100000
	s_addc_u32 s75, s63, 0
	v_readfirstlane_b32 s86, v114
	v_readfirstlane_b32 s87, v115
	s_add_u32 s86, s86, s9
	s_addc_u32 s87, s87, 0
	s_add_i32 s16, s2, 4
	s_lshl_b32 s16, s16, 16
	s_add_u32 s16, s14, s16
	s_addc_u32 s17, s15, 0
	s_add_i32 s0, s2, 0x2000
	s_lshl_b32 s1, s0, 13
	s_add_u32 s6, s40, s1
	s_addc_u32 s7, s41, 0
	s_lshl_b32 s1, s0, 12
	s_add_u32 s10, s44, s1
	s_addc_u32 s11, s45, 0
	v_readlane_b32 s9, v255, 5
	s_lshl_b32 s1, s9, 6
	v_readlane_b32 s90, v255, 0
	v_readlane_b32 s91, v255, 1
	s_sub_u32 s90, s90, 0xc8
	s_subb_u32 s91, s91, 0
	s_load_dwordx2 s[94:95], s[90:91], 0x78
	s_load_dwordx2 s[88:89], s[90:91], 0x80
	v_add_u32_e32 v70, s1, v170
	v_add_u32_e32 v70, 0x400, v70
	v_mul_u32_u24_e32 v151, 0x1556, v70
	v_lshrrev_b32_e32 v151, 16, v151
	v_lshlrev_b32_e32 v70, 4, v70
	v_lshl_add_u32 v70, v151, 6, v70
	v_add_u32_e32 v71, s1, v170
	v_add_u32_e32 v71, 0x800, v71
	v_mul_u32_u24_e32 v151, 0x1556, v71
	v_lshrrev_b32_e32 v151, 16, v151
	v_lshlrev_b32_e32 v71, 4, v71
	v_lshl_add_u32 v71, v151, 6, v71
	v_add_u32_e32 v72, s1, v170
	v_add_u32_e32 v72, 0x600, v72
	v_mul_u32_u24_e32 v151, 0x1556, v72
	v_lshrrev_b32_e32 v151, 16, v151
	v_lshlrev_b32_e32 v72, 4, v72
	v_lshl_add_u32 v72, v151, 6, v72
	global_load_dwordx4 v[158:161], v73, s[32:33]
	global_load_dwordx4 v[162:165], v73, s[50:51]
	global_load_dwordx4 v[166:169], v73, s[52:53]
	global_load_dwordx4 v[176:179], v73, s[54:55]
	global_load_dwordx4 v[180:183], v73, s[56:57]
	global_load_dwordx4 v[184:187], v73, s[60:61]
	global_load_dwordx4 v[212:215], v73, s[62:63]
	global_load_dwordx4 v[216:219], v73, s[74:75]
	global_load_dwordx4 v[224:227], v70, s[16:17]
	global_load_dwordx4 v[220:223], v73, s[86:87]
	global_load_dwordx4 v[228:231], v71, s[16:17]
	global_load_dwordx4 v[232:235], v72, s[16:17]
	s_waitcnt lgkmcnt(0)
	global_load_dwordx4 v[236:239], v73, s[94:95]
	global_load_dwordx4 v[240:243], v73, s[88:89]
	s_waitcnt vmcnt(13)
	v_pk_add_f32 v[252:253], v[158:159], 0 op_sel_hi:[1,0]
	v_pk_add_f32 v[148:149], v[160:161], 0 op_sel_hi:[1,0]
	s_waitcnt vmcnt(12)
	v_pk_add_f32 v[252:253], v[252:253], v[162:163]
	v_pk_add_f32 v[148:149], v[148:149], v[164:165]
	s_waitcnt vmcnt(11)
	v_pk_add_f32 v[252:253], v[252:253], v[166:167]
	v_pk_add_f32 v[148:149], v[148:149], v[168:169]
	s_waitcnt vmcnt(10)
	v_pk_add_f32 v[252:253], v[252:253], v[176:177]
	v_pk_add_f32 v[148:149], v[148:149], v[178:179]
	s_waitcnt vmcnt(9)
	v_pk_add_f32 v[252:253], v[252:253], v[180:181]
	v_pk_add_f32 v[148:149], v[148:149], v[182:183]
	s_waitcnt vmcnt(8)
	v_pk_add_f32 v[252:253], v[252:253], v[184:185]
	v_pk_add_f32 v[148:149], v[148:149], v[186:187]
	s_waitcnt vmcnt(7)
	v_pk_add_f32 v[252:253], v[252:253], v[212:213]
	v_pk_add_f32 v[148:149], v[148:149], v[214:215]
	s_waitcnt vmcnt(6)
	v_pk_add_f32 v[252:253], v[252:253], v[216:217]
	v_pk_add_f32 v[148:149], v[148:149], v[218:219]
	s_waitcnt vmcnt(5)
	v_pk_mul_f32 v[252:253], v[252:253], v[224:225]
	v_pk_mul_f32 v[148:149], v[148:149], v[226:227]
	s_waitcnt vmcnt(4)
	v_fma_f32 v66, v220, s3, v252
	v_fma_f32 v67, v221, s3, v253
	v_fma_f32 v68, v222, s3, v148
	v_fma_f32 v69, v223, s3, v149
	v_add_f32_e32 v151, v66, v67
	v_add_f32_e32 v155, v68, v69
	v_add_f32_e32 v153, v151, v155
	ds_bpermute_b32 v151, v99, v153
	s_waitcnt lgkmcnt(0)
	v_add_f32_e32 v153, v153, v151
	ds_bpermute_b32 v151, v101, v153
	s_waitcnt lgkmcnt(0)
	v_add_f32_e32 v153, v153, v151
	ds_bpermute_b32 v151, v103, v153
	s_waitcnt lgkmcnt(0)
	v_add_f32_e32 v153, v153, v151
	ds_bpermute_b32 v151, v105, v153
	s_waitcnt lgkmcnt(0)
	v_add_f32_e32 v153, v153, v151
	ds_bpermute_b32 v151, v107, v153
	s_waitcnt lgkmcnt(0)
	v_add_f32_e32 v153, v153, v151
	ds_bpermute_b32 v151, v119, v153
	s_waitcnt lgkmcnt(0)
	v_add_f32_e32 v153, v153, v151
	v_readlane_b32 s0, v255, 5
	s_lshl_b32 s0, s0, 2
	s_add_i32 s0, s0, 0x20040
	v_mov_b32_e32 v203, s0
	ds_write_b32 v203, v153
	s_waitcnt lgkmcnt(0)
	s_barrier
	v_mov_b32_e32 v204, 0x20040
	ds_read_b128 v[158:161], v204
	ds_read_b128 v[162:165], v204 offset:16
	s_waitcnt lgkmcnt(0)
	v_add_f32_e32 v153, 0, v158
	v_add_f32_e32 v153, v153, v159
	v_add_f32_e32 v153, v153, v160
	v_add_f32_e32 v153, v153, v161
	v_add_f32_e32 v153, v153, v162
	v_add_f32_e32 v153, v153, v163
	v_add_f32_e32 v153, v153, v164
	v_add_f32_e32 v153, v153, v165
	v_fmac_f32_e32 v66, 0xba000000, v153
	v_fmac_f32_e32 v67, 0xba000000, v153
	v_fmac_f32_e32 v68, 0xba000000, v153
	v_fmac_f32_e32 v69, 0xba000000, v153
	v_mul_f32_e32 v151, v67, v67
	v_fma_f32 v151, v66, v66, v151
	v_mul_f32_e32 v155, v69, v69
	v_fma_f32 v155, v68, v68, v155
	v_add_f32_e32 v157, v151, v155
	ds_bpermute_b32 v151, v99, v157
	s_waitcnt lgkmcnt(0)
	v_add_f32_e32 v157, v157, v151
	ds_bpermute_b32 v151, v101, v157
	s_waitcnt lgkmcnt(0)
	v_add_f32_e32 v157, v157, v151
	ds_bpermute_b32 v151, v103, v157
	s_waitcnt lgkmcnt(0)
	v_add_f32_e32 v157, v157, v151
	ds_bpermute_b32 v151, v105, v157
	s_waitcnt lgkmcnt(0)
	v_add_f32_e32 v157, v157, v151
	ds_bpermute_b32 v151, v107, v157
	s_waitcnt lgkmcnt(0)
	v_add_f32_e32 v157, v157, v151
	ds_bpermute_b32 v151, v119, v157
	s_waitcnt lgkmcnt(0)
	v_add_f32_e32 v157, v157, v151
	v_add_u32_e32 v203, 32, v203
	ds_write_b32 v203, v157
	s_waitcnt lgkmcnt(0)
	s_barrier
	ds_read_b128 v[158:161], v204 offset:32
	ds_read_b128 v[162:165], v204 offset:48
	s_waitcnt lgkmcnt(0)
	v_add_f32_e32 v157, 0, v158
	v_add_f32_e32 v157, v157, v159
	v_add_f32_e32 v157, v157, v160
	v_add_f32_e32 v157, v157, v161
	v_add_f32_e32 v157, v157, v162
	v_add_f32_e32 v157, v157, v163
	v_add_f32_e32 v157, v157, v164
	v_add_f32_e32 v157, v157, v165
	v_mov_b32_e32 v254, 0x3727c5ac
	v_fmamk_f32 v157, v157, 0x3a000000, v254
	v_mul_f32_e32 v151, 0x4f800000, v157
	s_mov_b32 s9, 0xf800000
	v_cmp_gt_f32_e32 vcc, s9, v157
	s_nop 1
	v_cndmask_b32_e32 v157, v157, v151, vcc
	v_sqrt_f32_e32 v151, v157
	s_nop 0
	v_add_u32_e32 v203, -1, v151
	v_fma_f32 v204, -v203, v151, v157
	v_cmp_ge_f32_e64 s[88:89], 0, v204
	v_add_u32_e32 v204, 1, v151
	s_nop 0
	v_cndmask_b32_e64 v203, v151, v203, s[88:89]
	v_fma_f32 v151, -v204, v151, v157
	v_cmp_lt_f32_e64 s[88:89], 0, v151
	s_nop 1
	v_cndmask_b32_e64 v151, v203, v204, s[88:89]
	v_mul_f32_e32 v203, 0x37800000, v151
	v_cndmask_b32_e32 v151, v151, v203, vcc
	v_mov_b32_e32 v203, 0x260
	v_cmp_class_f32_e32 vcc, v157, v203
	s_nop 1
	v_cndmask_b32_e32 v157, v151, v157, vcc
	v_div_scale_f32 v151, s[88:89], v157, v157, 1.0
	v_rcp_f32_e32 v203, v151
	s_nop 0
	v_fma_f32 v204, -v151, v203, 1.0
	v_fmac_f32_e32 v203, v204, v203
	v_div_scale_f32 v204, vcc, 1.0, v157, 1.0
	v_mul_f32_e32 v205, v204, v203
	v_fma_f32 v254, -v151, v205, v204
	v_fmac_f32_e32 v205, v254, v203
	v_fma_f32 v151, -v151, v205, v204
	v_div_fmas_f32 v151, v151, v203, v205
	v_div_fixup_f32 v155, v151, v157, 1.0
	s_waitcnt vmcnt(0)
	v_mul_f32_e32 v66, v66, v155
	v_mul_f32_e32 v67, v67, v155
	v_mul_f32_e32 v68, v68, v155
	v_mul_f32_e32 v69, v69, v155
	v_pk_fma_f32 v[66:67], v[236:237], v[66:67], v[240:241]
	v_pk_fma_f32 v[68:69], v[238:239], v[68:69], v[242:243]
	global_store_dwordx4 v73, v[66:69], s[6:7]
	v_pk_add_f32 v[228:229], v[228:229], 1.0 op_sel_hi:[1,0]
	v_pk_add_f32 v[230:231], v[230:231], 1.0 op_sel_hi:[1,0]
	v_pk_fma_f32 v[228:229], v[228:229], v[66:67], v[232:233]
	v_pk_fma_f32 v[230:231], v[230:231], v[68:69], v[234:235]
	v_cvt_pk_bf16_f32 v228, v228, v229
	v_cvt_pk_bf16_f32 v229, v230, v231
	global_store_dwordx2 v74, v[228:229], s[10:11]
.Lp6_nosample:
.LBB0_755:
	s_waitcnt vmcnt(0)
	s_barrier
	s_mov_b64 s[6:7], exec
	v_readlane_b32 s0, v255, 3
	v_readlane_b32 s1, v255, 4
	s_and_b64 s[0:1], s[6:7], s[0:1]
	s_mov_b64 exec, s[0:1]
	s_cbranch_execz .LBB0_807
	v_mov_b32_e32 v2, 0x20000
	ds_read_b32 v6, v2
	ds_read_b32 v7, v2 offset:4
	v_readlane_b32 s0, v255, 2
	s_and_b32 s0, s0, 7
	s_lshl_b32 s0, s0, 7
	s_add_i32 s0, s0, 0x3600
	v_mov_b32_e32 v8, s0
	v_mov_b32_e32 v9, 1
	s_mov_b32 s11, 7
	s_mov_b32 s10, 0
	global_atomic_add v10, v8, v9, s[70:71] sc0
	s_waitcnt vmcnt(0) lgkmcnt(0)
	v_mul_lo_u32 v11, v6, s11
	v_add_u32_e32 v10, 1, v10
	v_cmp_eq_u32_e32 vcc, v10, v11
	v_mul_lo_u32 v11, v7, s11
	s_cbranch_vccz .Lxb7_inv
	buffer_wbl2 sc1
	v_mov_b32_e32 v2, 0x3a00
	s_waitcnt vmcnt(0)
	global_atomic_add v2, v9, s[70:71]
	global_atomic_add v2, v9, s[70:71] offset:128
	global_atomic_add v2, v9, s[70:71] offset:256
	global_atomic_add v2, v9, s[70:71] offset:384
	global_atomic_add v2, v9, s[70:71] offset:512
	global_atomic_add v2, v9, s[70:71] offset:640
	global_atomic_add v2, v9, s[70:71] offset:768
	global_atomic_add v2, v9, s[70:71] offset:896
.Lxb7_inv:
	buffer_inv sc1
.Lxb7_poll:
	global_load_dword v10, v8, s[70:71] offset:1024 sc1
	s_add_i32 s10, s10, 1
	s_waitcnt vmcnt(0)
	v_cmp_ge_u32_e32 vcc, v10, v11
	s_cbranch_vccnz .Lxb7_done
	s_sleep 1
	s_cmp_lt_u32 s10, 0x8000
	s_cbranch_scc1 .Lxb7_poll
.Lxb7_done:
.LBB0_807:
	s_or_b64 exec, exec, s[6:7]
	v_readlane_b32 s0, v255, 12
	v_readlane_b32 s1, v255, 13
	s_andn2_b64 vcc, exec, s[0:1]
	v_readfirstlane_b32 s33, v0
	s_waitcnt lgkmcnt(0)
	s_barrier
	s_cbranch_vccnz .LBB0_839
	s_ashr_i32 s0, s2, 31
	s_lshr_b32 s1, s0, 29
	s_add_i32 s1, s2, s1
	s_and_b32 s3, s1, -8
	s_sub_i32 s8, s2, s3
	s_cmp_gt_i32 s8, -1
	s_cbranch_scc0 .LBB0_810
	s_lshl_b32 s3, s8, 7
	s_cbranch_execz .LBB0_811
	s_branch .LBB0_812

.LBB0_864:
	s_waitcnt vmcnt(0)
	s_barrier
	s_mov_b64 s[6:7], exec
	v_readlane_b32 s0, v255, 3
	v_readlane_b32 s1, v255, 4
	v_readlane_b32 s82, v255, 6
	s_and_b64 s[0:1], s[6:7], s[0:1]
	v_readlane_b32 s83, v255, 7
	s_mov_b64 exec, s[0:1]
	s_cbranch_execz .LBB0_916
	v_mov_b32_e32 v2, 0x20000
	ds_read_b32 v6, v2
	ds_read_b32 v7, v2 offset:4
	v_readlane_b32 s0, v255, 2
	s_and_b32 s0, s0, 7
	s_lshl_b32 s0, s0, 7
	s_add_i32 s0, s0, 0x3600
	v_mov_b32_e32 v8, s0
	v_mov_b32_e32 v9, 1
	s_mov_b32 s11, 8
	s_mov_b32 s10, 0
	global_atomic_add v10, v8, v9, s[70:71] sc0
	s_waitcnt vmcnt(0) lgkmcnt(0)
	v_mul_lo_u32 v11, v6, s11
	v_add_u32_e32 v10, 1, v10
	v_cmp_eq_u32_e32 vcc, v10, v11
	v_mul_lo_u32 v11, v7, s11
	s_cbranch_vccz .Lxb8_inv
	buffer_wbl2 sc1
	v_mov_b32_e32 v2, 0x3a00
	s_waitcnt vmcnt(0)
	global_atomic_add v2, v9, s[70:71]
	global_atomic_add v2, v9, s[70:71] offset:128
	global_atomic_add v2, v9, s[70:71] offset:256
	global_atomic_add v2, v9, s[70:71] offset:384
	global_atomic_add v2, v9, s[70:71] offset:512
	global_atomic_add v2, v9, s[70:71] offset:640
	global_atomic_add v2, v9, s[70:71] offset:768
	global_atomic_add v2, v9, s[70:71] offset:896
.Lxb8_inv:
	buffer_inv sc1
.Lxb8_poll:
	global_load_dword v10, v8, s[70:71] offset:1024 sc1
	s_add_i32 s10, s10, 1
	s_waitcnt vmcnt(0)
	v_cmp_ge_u32_e32 vcc, v10, v11
	s_cbranch_vccnz .Lxb8_done
	s_sleep 1
	s_cmp_lt_u32 s10, 0x8000
	s_cbranch_scc1 .Lxb8_poll
.Lxb8_done:
.LBB0_916:
	s_or_b64 exec, exec, s[6:7]
	v_readlane_b32 s0, v255, 18
	v_readlane_b32 s1, v255, 19
	v_readfirstlane_b32 s9, v0
	v_lshl_or_b32 v184, v197, 14, v196
	s_and_b64 vcc, exec, s[0:1]
	v_lshl_or_b32 v186, v198, 14, v196
	s_waitcnt lgkmcnt(0)
	s_barrier
	s_cbranch_vccnz .LBB0_948
	s_ashr_i32 s0, s2, 31
	s_lshr_b32 s1, s0, 29
	s_add_i32 s8, s2, s1
	s_and_b32 s1, s8, -8
	s_sub_i32 s1, s2, s1
	s_cmp_gt_i32 s1, -1
	s_cbranch_scc0 .LBB0_919
	s_lshl_b32 s3, s1, 5
	s_ashr_i32 s6, s8, 3
	s_cbranch_execz .LBB0_920
	s_branch .LBB0_921

.LBB0_953:
	s_waitcnt vmcnt(0)
	s_waitcnt vmcnt(0)
	s_barrier
	s_mov_b64 s[2:3], exec
	v_readlane_b32 s0, v255, 3
	v_readlane_b32 s1, v255, 4
	s_and_b64 s[0:1], s[2:3], s[0:1]
	s_mov_b64 exec, s[0:1]
	s_cbranch_execz .LBB0_1005
	v_mov_b32_e32 v2, 0x20000
	ds_read_b32 v6, v2
	ds_read_b32 v7, v2 offset:4
	v_readlane_b32 s0, v255, 2
	s_and_b32 s0, s0, 7
	s_lshl_b32 s0, s0, 7
	s_add_i32 s0, s0, 0x3600
	v_mov_b32_e32 v8, s0
	v_mov_b32_e32 v9, 1
	s_mov_b32 s11, 9
	s_mov_b32 s10, 0
	global_atomic_add v10, v8, v9, s[70:71] sc0
	s_waitcnt vmcnt(0) lgkmcnt(0)
	v_mul_lo_u32 v11, v6, s11
	v_add_u32_e32 v10, 1, v10
	v_cmp_eq_u32_e32 vcc, v10, v11
	v_mul_lo_u32 v11, v7, s11
	s_cbranch_vccz .Lxb9_inv
	buffer_wbl2 sc1
	v_mov_b32_e32 v2, 0x3a00
	s_waitcnt vmcnt(0)
	global_atomic_add v2, v9, s[70:71]
	global_atomic_add v2, v9, s[70:71] offset:128
	global_atomic_add v2, v9, s[70:71] offset:256
	global_atomic_add v2, v9, s[70:71] offset:384
	global_atomic_add v2, v9, s[70:71] offset:512
	global_atomic_add v2, v9, s[70:71] offset:640
	global_atomic_add v2, v9, s[70:71] offset:768
	global_atomic_add v2, v9, s[70:71] offset:896
.Lxb9_inv:
	buffer_inv sc1
.Lxb9_poll:
	global_load_dword v10, v8, s[70:71] offset:1024 sc1
	s_add_i32 s10, s10, 1
	s_waitcnt vmcnt(0)
	v_cmp_ge_u32_e32 vcc, v10, v11
	s_cbranch_vccnz .Lxb9_done
	s_sleep 1
	s_cmp_lt_u32 s10, 0x8000
	s_cbranch_scc1 .Lxb9_poll
.Lxb9_done:
.LBB0_1005:
	s_or_b64 exec, exec, s[2:3]
	v_lshlrev_b32_e32 v64, 4, v170
	v_mov_b32_e32 v65, 0
	v_lshl_add_u64 v[32:33], s[26:27], 0, v[64:65]
	s_movk_i32 s0, 0x1000
	v_add_co_u32_e32 v66, vcc, s0, v32
	v_lshl_add_u64 v[34:35], s[28:29], 0, v[64:65]
	s_nop 0
	v_addc_co_u32_e32 v67, vcc, 0, v33, vcc
	v_add_co_u32_e32 v68, vcc, s0, v34
	s_waitcnt lgkmcnt(0)
	s_barrier
	global_load_dwordx4 v[0:3], v64, s[26:27]
	global_load_dwordx4 v[4:7], v64, s[28:29]
	global_load_dwordx4 v[8:11], v64, s[26:27] offset:1024
	global_load_dwordx4 v[12:15], v64, s[28:29] offset:1024
	global_load_dwordx4 v[16:19], v64, s[26:27] offset:2048
	global_load_dwordx4 v[20:23], v64, s[28:29] offset:2048
	global_load_dwordx4 v[24:27], v64, s[26:27] offset:3072
	global_load_dwordx4 v[28:31], v64, s[28:29] offset:3072
	v_addc_co_u32_e32 v69, vcc, 0, v35, vcc
	global_load_dwordx4 v[32:35], v[66:67], off
	global_load_dwordx4 v[36:39], v[66:67], off offset:1024
	global_load_dwordx4 v[40:43], v[68:69], off
	global_load_dwordx4 v[44:47], v[68:69], off offset:1024
	global_load_dwordx4 v[48:51], v[66:67], off offset:2048
	global_load_dwordx4 v[52:55], v[66:67], off offset:3072
	global_load_dwordx4 v[56:59], v[68:69], off offset:2048
	global_load_dwordx4 v[60:63], v[68:69], off offset:3072
	v_or_b32_e32 v66, 0x2800, v171
	s_mov_b32 s0, 0x5555556
	v_mul_hi_u32 v67, v66, s0
	v_lshl_add_u32 v66, v67, 4, v66
	v_or_b32_e32 v67, 0x2900, v171
	v_mul_hi_u32 v68, v67, s0
	v_lshl_add_u32 v68, v68, 4, v67
	v_or_b32_e32 v67, 0x2a00, v171
	v_mul_hi_u32 v69, v67, s0
	v_lshl_add_u32 v70, v69, 4, v67
	v_or_b32_e32 v67, 0x2b00, v171
	v_mul_hi_u32 v69, v67, s0
	v_lshl_add_u32 v72, v69, 4, v67
	v_or_b32_e32 v67, 0x2c00, v171
	v_mul_hi_u32 v69, v67, s0
	v_lshl_add_u32 v74, v69, 4, v67
	v_or_b32_e32 v67, 0x2d00, v171
	v_mul_hi_u32 v69, v67, s0
	v_lshl_add_u32 v76, v69, 4, v67
	v_or_b32_e32 v67, 0x2e00, v171
	v_mul_hi_u32 v69, v67, s0
	v_lshl_add_u32 v78, v69, 4, v67
	v_or_b32_e32 v67, 0x2f00, v171
	v_mul_hi_u32 v69, v67, s0
	v_lshl_add_u64 v[98:99], s[24:25], 0, v[64:65]
	s_mov_b64 s[0:1], 0x1000
	v_lshl_add_u64 v[100:101], v[98:99], 0, s[0:1]
	s_mov_b64 s[0:1], 0x1400
	v_lshl_add_u64 v[102:103], v[98:99], 0, s[0:1]
	s_mov_b64 s[0:1], 0x1800
	v_lshl_add_u32 v80, v69, 4, v67
	v_lshl_add_u64 v[104:105], v[98:99], 0, s[0:1]
	s_mov_b64 s[0:1], 0x1c00
	s_mov_b32 s3, 0
	v_lshl_add_u64 v[96:97], s[30:31], 0, v[64:65]
	v_lshl_add_u64 v[106:107], v[98:99], 0, s[0:1]
	s_mov_b32 s7, 0x100000
	s_mov_b32 s18, 0x200000
	s_mov_b32 s19, 0x300000
	s_mov_b32 s20, 0x400000
	s_mov_b32 s21, 0x500000
	s_mov_b32 s22, 0x600000
	s_mov_b32 s23, 0x700000
	v_lshlrev_b32_e32 v136, 2, v66
	s_mov_b32 s6, 0x3f9837f0
	v_lshlrev_b32_e32 v137, 2, v68
	v_lshlrev_b32_e32 v138, 2, v70
	v_lshlrev_b32_e32 v139, 2, v72
	v_lshlrev_b32_e32 v140, 2, v74
	v_lshlrev_b32_e32 v141, 2, v76
	v_lshlrev_b32_e32 v142, 2, v78
	v_lshlrev_b32_e32 v143, 2, v80
	v_mov_b32_e32 v144, 0x3727c5ac
	s_mov_b32 s24, 0xf800000
	v_mov_b32_e32 v145, 0x260
	s_mov_b32 s25, s68
	s_mov_b32 s26, 0
	s_branch .LBB0_1009
